# baseline (speedup 1.0000x reference)
; template <int N, int K, int EPI>
; __device__ __forceinline__ void gemm_phase(const bf16* __restrict__ A, const bf16* __restrict__ Bt, float* __restrict__ outf, bf16* __restrict__ outb,
;                            const float* __restrict__ ropec, const int W) {
;     ...
;       char* obase = (char*)(outb + (size_t)brow * N + bcol);
; #pragma unroll
;       for (int ai = 0; ai < 2; ++ai)
; #pragma unroll
;         for (int bj = 0; bj < 2; ++bj)
; #pragma unroll
;           for (int m = 0; m < 4; ++m) {
;             const unsigned lrow = ai * HALF + wr * 64 + m * 16 + efr;
;             const unsigned lcol = bj * HALF + wcb + efq * 8;
;             const f32x4 v0 = acc[ai][bj][m][0], v1 = acc[ai][bj][m][1];
;             if (EPI == EPI_RES) {
;               u32x4* d = (u32x4*)(obase + (size_t)((lrow * N + lcol) * 2u));
;               const u32x4 t = *d;
;               const f32x4 r0 = bf4_to_f32(u32x2{t[0], t[1]}) + v0, r1 = bf4_to_f32(u32x2{t[2], t[3]}) + v1;
;               u32x4 w = {cvtpk(r0[0], r0[1]), cvtpk(r0[2], r0[3]), cvtpk(r1[0], r1[1]), cvtpk(r1[2], r1[3])};
;               *d = w;
;     ...
;     asm volatile("s_waitcnt vmcnt(0) lgkmcnt(0)" ::: "memory");
;     __syncthreads();
.LBB0_151:
	v_mbcnt_lo_u32_b32 v133, -1, 0
	v_mbcnt_hi_u32_b32 v133, -1, v133
	s_lshl_b64 s[6:7], s[80:81], 1
	v_lshrrev_b32_e32 v132, 1, v133
	v_lshlrev_b32_e32 v133, 10, v133
	s_add_u32 s80, s66, s6
	v_and_b32_e32 v133, 0x3c00, v133
	s_addc_u32 s81, s67, s7
	s_lshl_b64 s[6:7], s[90:91], 1
	v_and_or_b32 v132, v132, 24, s4
	v_or_b32_e32 v133, s5, v133
	s_add_u32 s90, s80, s6
	v_or_b32_e32 v158, v133, v132
	s_addc_u32 s91, s81, s7
	v_lshlrev_b32_e32 v164, 1, v158
	global_load_dwordx4 v[158:161], v164, s[90:91]
	s_add_i32 s96, s96, s33
	s_cmpk_lt_i32 s96, 0x200
	s_waitcnt vmcnt(0)
	v_lshlrev_b32_e32 v162, 16, v158
	v_and_b32_e32 v163, 0xffff0000, v158
	v_lshlrev_b32_e32 v158, 16, v159
	v_and_b32_e32 v159, 0xffff0000, v159
	v_pk_add_f32 v[126:127], v[126:127], v[158:159]
	v_lshlrev_b32_e32 v158, 16, v160
	v_and_b32_e32 v159, 0xffff0000, v160
	v_lshlrev_b32_e32 v160, 16, v161
	v_and_b32_e32 v161, 0xffff0000, v161
	v_pk_add_f32 v[124:125], v[124:125], v[162:163]
	v_pk_add_f32 v[160:161], v[122:123], v[160:161]
	v_pk_add_f32 v[122:123], v[120:121], v[158:159]
	v_cvt_pk_bf16_f32 v120, v124, v125
	v_cvt_pk_bf16_f32 v121, v126, v127
	s_nop 0
	v_cvt_pk_bf16_f32 v122, v122, v123
	v_cvt_pk_bf16_f32 v123, v160, v161
	global_store_dwordx4 v164, v[120:123], s[90:91] sc1
	s_nop 1
	v_or_b32_e32 v120, 0x4000, v133
	v_or_b32_e32 v121, v120, v132
	v_lshlrev_b32_e32 v121, 1, v121
	global_load_dwordx4 v[122:125], v121, s[90:91]
	s_waitcnt vmcnt(0)
	v_lshlrev_b32_e32 v126, 16, v122
	v_and_b32_e32 v127, 0xffff0000, v122
	v_lshlrev_b32_e32 v122, 16, v123
	v_and_b32_e32 v123, 0xffff0000, v123
	v_pk_add_f32 v[118:119], v[118:119], v[122:123]
	v_lshlrev_b32_e32 v122, 16, v124
	v_and_b32_e32 v123, 0xffff0000, v124
	v_lshlrev_b32_e32 v124, 16, v125
	v_and_b32_e32 v125, 0xffff0000, v125
	v_pk_add_f32 v[116:117], v[116:117], v[126:127]
	v_pk_add_f32 v[124:125], v[114:115], v[124:125]
	v_pk_add_f32 v[114:115], v[112:113], v[122:123]
	v_cvt_pk_bf16_f32 v112, v116, v117
	v_cvt_pk_bf16_f32 v113, v118, v119
	s_nop 0
	v_cvt_pk_bf16_f32 v114, v114, v115
	v_cvt_pk_bf16_f32 v115, v124, v125
	global_store_dwordx4 v121, v[112:115], s[90:91] sc1
	s_nop 1
	v_or_b32_e32 v112, 0x8000, v133
	v_or_b32_e32 v113, v112, v132
	v_lshlrev_b32_e32 v113, 1, v113
	global_load_dwordx4 v[114:117], v113, s[90:91]
	s_waitcnt vmcnt(0)
	v_lshlrev_b32_e32 v118, 16, v114
	v_and_b32_e32 v119, 0xffff0000, v114
	v_lshlrev_b32_e32 v114, 16, v115
	v_and_b32_e32 v115, 0xffff0000, v115
	v_pk_add_f32 v[110:111], v[110:111], v[114:115]
	v_lshlrev_b32_e32 v114, 16, v116
	v_and_b32_e32 v115, 0xffff0000, v116
	v_lshlrev_b32_e32 v116, 16, v117
	v_and_b32_e32 v117, 0xffff0000, v117
	v_pk_add_f32 v[108:109], v[108:109], v[118:119]
	v_pk_add_f32 v[116:117], v[106:107], v[116:117]
	v_pk_add_f32 v[106:107], v[104:105], v[114:115]
	v_cvt_pk_bf16_f32 v104, v108, v109
	v_cvt_pk_bf16_f32 v105, v110, v111
	s_nop 0
	v_cvt_pk_bf16_f32 v106, v106, v107
	v_cvt_pk_bf16_f32 v107, v116, v117
	global_store_dwordx4 v113, v[104:107], s[90:91] sc1
	s_nop 1
	v_or_b32_e32 v104, 0xc000, v133
	v_or_b32_e32 v105, v104, v132
	v_lshlrev_b32_e32 v105, 1, v105
	global_load_dwordx4 v[106:109], v105, s[90:91]
	s_waitcnt vmcnt(0)
	v_lshlrev_b32_e32 v110, 16, v106
	v_and_b32_e32 v111, 0xffff0000, v106
	v_lshlrev_b32_e32 v106, 16, v107
	v_and_b32_e32 v107, 0xffff0000, v107
	v_pk_add_f32 v[102:103], v[102:103], v[106:107]
	v_lshlrev_b32_e32 v106, 16, v108
	v_and_b32_e32 v107, 0xffff0000, v108
	v_lshlrev_b32_e32 v108, 16, v109
	v_and_b32_e32 v109, 0xffff0000, v109
	v_pk_add_f32 v[100:101], v[100:101], v[110:111]
	v_pk_add_f32 v[108:109], v[98:99], v[108:109]
	v_pk_add_f32 v[98:99], v[96:97], v[106:107]
	v_cvt_pk_bf16_f32 v96, v100, v101
	v_cvt_pk_bf16_f32 v97, v102, v103
	s_nop 0
	v_cvt_pk_bf16_f32 v98, v98, v99
	v_cvt_pk_bf16_f32 v99, v108, v109
	global_store_dwordx4 v105, v[96:99], s[90:91] sc1
	s_nop 1
	v_or_b32_e32 v96, 0x80, v132
	v_or_b32_e32 v97, v96, v133
	v_lshlrev_b32_e32 v97, 1, v97
	global_load_dwordx4 v[98:101], v97, s[90:91]
	s_waitcnt vmcnt(0)
	v_lshlrev_b32_e32 v102, 16, v98
	v_and_b32_e32 v103, 0xffff0000, v98
	v_lshlrev_b32_e32 v98, 16, v99
	v_and_b32_e32 v99, 0xffff0000, v99
	v_pk_add_f32 v[94:95], v[94:95], v[98:99]
	v_lshlrev_b32_e32 v98, 16, v100
	v_and_b32_e32 v99, 0xffff0000, v100
	v_lshlrev_b32_e32 v100, 16, v101
	v_and_b32_e32 v101, 0xffff0000, v101
	v_pk_add_f32 v[92:93], v[92:93], v[102:103]
	v_pk_add_f32 v[100:101], v[90:91], v[100:101]
	v_pk_add_f32 v[90:91], v[88:89], v[98:99]
	v_cvt_pk_bf16_f32 v88, v92, v93
	v_cvt_pk_bf16_f32 v89, v94, v95
	s_nop 0
	v_cvt_pk_bf16_f32 v90, v90, v91
	v_cvt_pk_bf16_f32 v91, v100, v101
	global_store_dwordx4 v97, v[88:91], s[90:91] sc1
	s_nop 1
	v_or_b32_e32 v88, v120, v96
	v_lshlrev_b32_e32 v94, 1, v88
	global_load_dwordx4 v[88:91], v94, s[90:91]
	s_waitcnt vmcnt(0)
	v_lshlrev_b32_e32 v92, 16, v88
	v_and_b32_e32 v93, 0xffff0000, v88
	v_lshlrev_b32_e32 v88, 16, v89
	v_and_b32_e32 v89, 0xffff0000, v89
	v_pk_add_f32 v[86:87], v[86:87], v[88:89]
	v_lshlrev_b32_e32 v88, 16, v90
	v_and_b32_e32 v89, 0xffff0000, v90
	v_lshlrev_b32_e32 v90, 16, v91
	v_and_b32_e32 v91, 0xffff0000, v91
	v_pk_add_f32 v[84:85], v[84:85], v[92:93]
	v_pk_add_f32 v[90:91], v[82:83], v[90:91]
	v_pk_add_f32 v[82:83], v[80:81], v[88:89]
	v_cvt_pk_bf16_f32 v80, v84, v85
	v_cvt_pk_bf16_f32 v81, v86, v87
	s_nop 0
	v_cvt_pk_bf16_f32 v82, v82, v83
	v_cvt_pk_bf16_f32 v83, v90, v91
	global_store_dwordx4 v94, v[80:83], s[90:91] sc1
	s_nop 1
	v_or_b32_e32 v80, v112, v96
	v_lshlrev_b32_e32 v86, 1, v80
	global_load_dwordx4 v[80:83], v86, s[90:91]
	s_waitcnt vmcnt(0)
; template <int N, int K, int EPI>
; __device__ __forceinline__ void gemm_phase(const bf16* __restrict__ A, const bf16* __restrict__ Bt, float* __restrict__ outf, bf16* __restrict__ outb,
;                            const float* __restrict__ ropec, const int W) {
;     ...
;       char* obase = (char*)(outb + (size_t)brow * N + bcol);
; #pragma unroll
;       for (int ai = 0; ai < 2; ++ai)
; #pragma unroll
;         for (int bj = 0; bj < 2; ++bj)
; #pragma unroll
;           for (int m = 0; m < 4; ++m) {
;             const unsigned lrow = ai * HALF + wr * 64 + m * 16 + efr;
;             const unsigned lcol = bj * HALF + wcb + efq * 8;
;             const f32x4 v0 = acc[ai][bj][m][0], v1 = acc[ai][bj][m][1];
;             if (EPI == EPI_RES) {
;               u32x4* d = (u32x4*)(obase + (size_t)((lrow * N + lcol) * 2u));
;               const u32x4 t = *d;
;               const f32x4 r0 = bf4_to_f32(u32x2{t[0], t[1]}) + v0, r1 = bf4_to_f32(u32x2{t[2], t[3]}) + v1;
;               u32x4 w = {cvtpk(r0[0], r0[1]), cvtpk(r0[2], r0[3]), cvtpk(r1[0], r1[1]), cvtpk(r1[2], r1[3])};
;               *d = w;
	v_lshlrev_b32_e32 v84, 16, v80
	v_and_b32_e32 v85, 0xffff0000, v80
	v_lshlrev_b32_e32 v80, 16, v81
	v_and_b32_e32 v81, 0xffff0000, v81
	v_pk_add_f32 v[78:79], v[78:79], v[80:81]
	v_lshlrev_b32_e32 v80, 16, v82
	v_and_b32_e32 v81, 0xffff0000, v82
	v_lshlrev_b32_e32 v82, 16, v83
	v_and_b32_e32 v83, 0xffff0000, v83
	v_pk_add_f32 v[76:77], v[76:77], v[84:85]
	v_pk_add_f32 v[82:83], v[74:75], v[82:83]
	v_pk_add_f32 v[74:75], v[72:73], v[80:81]
	v_cvt_pk_bf16_f32 v72, v76, v77
	v_cvt_pk_bf16_f32 v73, v78, v79
	s_nop 0
	v_cvt_pk_bf16_f32 v74, v74, v75
	v_cvt_pk_bf16_f32 v75, v82, v83
	global_store_dwordx4 v86, v[72:75], s[90:91] sc1
	s_nop 1
	v_or_b32_e32 v72, v104, v96
	v_lshlrev_b32_e32 v78, 1, v72
	global_load_dwordx4 v[72:75], v78, s[90:91]
	s_waitcnt vmcnt(0)
	v_lshlrev_b32_e32 v76, 16, v72
	v_and_b32_e32 v77, 0xffff0000, v72
	v_lshlrev_b32_e32 v72, 16, v73
	v_and_b32_e32 v73, 0xffff0000, v73
	v_pk_add_f32 v[70:71], v[70:71], v[72:73]
	v_lshlrev_b32_e32 v72, 16, v74
	v_and_b32_e32 v73, 0xffff0000, v74
	v_lshlrev_b32_e32 v74, 16, v75
	v_and_b32_e32 v75, 0xffff0000, v75
	v_pk_add_f32 v[68:69], v[68:69], v[76:77]
	v_pk_add_f32 v[74:75], v[66:67], v[74:75]
	v_pk_add_f32 v[66:67], v[64:65], v[72:73]
	v_cvt_pk_bf16_f32 v64, v68, v69
	v_cvt_pk_bf16_f32 v65, v70, v71
	s_nop 0
	v_cvt_pk_bf16_f32 v66, v66, v67
	v_cvt_pk_bf16_f32 v67, v74, v75
	global_store_dwordx4 v78, v[64:67], s[90:91] sc1
	s_nop 1
	v_add_u32_e32 v64, 0x20000, v133
	v_or_b32_e32 v65, v64, v132
	v_lshlrev_b32_e32 v65, 1, v65
	global_load_dwordx4 v[66:69], v65, s[90:91]
	s_waitcnt vmcnt(0)
	v_lshlrev_b32_e32 v70, 16, v66
	v_and_b32_e32 v71, 0xffff0000, v66
	v_lshlrev_b32_e32 v66, 16, v67
	v_and_b32_e32 v67, 0xffff0000, v67
	v_pk_add_f32 v[62:63], v[62:63], v[66:67]
	v_lshlrev_b32_e32 v66, 16, v68
	v_and_b32_e32 v67, 0xffff0000, v68
	v_lshlrev_b32_e32 v68, 16, v69
	v_and_b32_e32 v69, 0xffff0000, v69
	v_pk_add_f32 v[60:61], v[60:61], v[70:71]
	v_pk_add_f32 v[68:69], v[58:59], v[68:69]
	v_pk_add_f32 v[58:59], v[56:57], v[66:67]
	v_cvt_pk_bf16_f32 v56, v60, v61
	v_cvt_pk_bf16_f32 v57, v62, v63
	s_nop 0
	v_cvt_pk_bf16_f32 v58, v58, v59
	v_cvt_pk_bf16_f32 v59, v68, v69
	global_store_dwordx4 v65, v[56:59], s[90:91] sc1
	s_nop 1
	v_add_u32_e32 v56, 0x24000, v133
	v_or_b32_e32 v57, v56, v132
	v_lshlrev_b32_e32 v57, 1, v57
	global_load_dwordx4 v[58:61], v57, s[90:91]
	s_waitcnt vmcnt(0)
	v_lshlrev_b32_e32 v62, 16, v58
	v_and_b32_e32 v63, 0xffff0000, v58
	v_lshlrev_b32_e32 v58, 16, v59
	v_and_b32_e32 v59, 0xffff0000, v59
	v_pk_add_f32 v[54:55], v[54:55], v[58:59]
	v_lshlrev_b32_e32 v58, 16, v60
	v_and_b32_e32 v59, 0xffff0000, v60
	v_lshlrev_b32_e32 v60, 16, v61
	v_and_b32_e32 v61, 0xffff0000, v61
	v_pk_add_f32 v[52:53], v[52:53], v[62:63]
	v_pk_add_f32 v[60:61], v[50:51], v[60:61]
	v_pk_add_f32 v[50:51], v[48:49], v[58:59]
	v_cvt_pk_bf16_f32 v48, v52, v53
	v_cvt_pk_bf16_f32 v49, v54, v55
	s_nop 0
	v_cvt_pk_bf16_f32 v50, v50, v51
	v_cvt_pk_bf16_f32 v51, v60, v61
	global_store_dwordx4 v57, v[48:51], s[90:91] sc1
	s_nop 1
	v_add_u32_e32 v48, 0x28000, v133
	v_or_b32_e32 v49, v48, v132
	v_lshlrev_b32_e32 v49, 1, v49
	global_load_dwordx4 v[50:53], v49, s[90:91]
	s_waitcnt vmcnt(0)
	v_lshlrev_b32_e32 v54, 16, v50
	v_and_b32_e32 v55, 0xffff0000, v50
	v_lshlrev_b32_e32 v50, 16, v51
	v_and_b32_e32 v51, 0xffff0000, v51
	v_pk_add_f32 v[46:47], v[46:47], v[50:51]
	v_lshlrev_b32_e32 v50, 16, v52
	v_and_b32_e32 v51, 0xffff0000, v52
	v_lshlrev_b32_e32 v52, 16, v53
	v_and_b32_e32 v53, 0xffff0000, v53
	v_pk_add_f32 v[44:45], v[44:45], v[54:55]
	v_pk_add_f32 v[52:53], v[42:43], v[52:53]
	v_pk_add_f32 v[42:43], v[40:41], v[50:51]
	v_cvt_pk_bf16_f32 v40, v44, v45
	v_cvt_pk_bf16_f32 v41, v46, v47
	s_nop 0
	v_cvt_pk_bf16_f32 v42, v42, v43
	v_cvt_pk_bf16_f32 v43, v52, v53
	global_store_dwordx4 v49, v[40:43], s[90:91] sc1
	s_nop 1
	v_add_u32_e32 v40, 0x2c000, v133
	v_or_b32_e32 v41, v40, v132
	v_lshlrev_b32_e32 v41, 1, v41
	global_load_dwordx4 v[42:45], v41, s[90:91]
	s_waitcnt vmcnt(0)
; template <int N, int K, int EPI>
; __device__ __forceinline__ void gemm_phase(const bf16* __restrict__ A, const bf16* __restrict__ Bt, float* __restrict__ outf, bf16* __restrict__ outb,
;                            const float* __restrict__ ropec, const int W) {
;     ...
;       char* obase = (char*)(outb + (size_t)brow * N + bcol);
; #pragma unroll
;       for (int ai = 0; ai < 2; ++ai)
; #pragma unroll
;         for (int bj = 0; bj < 2; ++bj)
; #pragma unroll
;           for (int m = 0; m < 4; ++m) {
;             const unsigned lrow = ai * HALF + wr * 64 + m * 16 + efr;
;             const unsigned lcol = bj * HALF + wcb + efq * 8;
;             const f32x4 v0 = acc[ai][bj][m][0], v1 = acc[ai][bj][m][1];
;             if (EPI == EPI_RES) {
;               u32x4* d = (u32x4*)(obase + (size_t)((lrow * N + lcol) * 2u));
;               const u32x4 t = *d;
;               const f32x4 r0 = bf4_to_f32(u32x2{t[0], t[1]}) + v0, r1 = bf4_to_f32(u32x2{t[2], t[3]}) + v1;
;               u32x4 w = {cvtpk(r0[0], r0[1]), cvtpk(r0[2], r0[3]), cvtpk(r1[0], r1[1]), cvtpk(r1[2], r1[3])};
;               *d = w;
;             } else {
;               const float a0 = fmaxf(v0[0], 0.f), a1 = fmaxf(v0[1], 0.f), a2 = fmaxf(v0[2], 0.f), a3 = fmaxf(v0[3], 0.f);
;               const float b0 = fmaxf(v1[0], 0.f), b1 = fmaxf(v1[1], 0.f), b2 = fmaxf(v1[2], 0.f), b3 = fmaxf(v1[3], 0.f);
;               u32x4 w = {cvtpk(a0 * a0, a1 * a1), cvtpk(a2 * a2, a3 * a3), cvtpk(b0 * b0, b1 * b1), cvtpk(b2 * b2, b3 * b3)};
;               *(u32x4*)(obase + (size_t)((lrow * N + lcol) * 2u)) = w;
;             }
;           }
;     }
;     asm volatile("s_waitcnt vmcnt(0) lgkmcnt(0)" ::: "memory");
;     __syncthreads();
	v_lshlrev_b32_e32 v46, 16, v42
	v_and_b32_e32 v47, 0xffff0000, v42
	v_lshlrev_b32_e32 v42, 16, v43
	v_and_b32_e32 v43, 0xffff0000, v43
	v_pk_add_f32 v[38:39], v[38:39], v[42:43]
	v_lshlrev_b32_e32 v42, 16, v44
	v_and_b32_e32 v43, 0xffff0000, v44
	v_lshlrev_b32_e32 v44, 16, v45
	v_and_b32_e32 v45, 0xffff0000, v45
	v_pk_add_f32 v[36:37], v[36:37], v[46:47]
	v_pk_add_f32 v[44:45], v[34:35], v[44:45]
	v_pk_add_f32 v[34:35], v[32:33], v[42:43]
	v_cvt_pk_bf16_f32 v32, v36, v37
	v_cvt_pk_bf16_f32 v33, v38, v39
	s_nop 0
	v_cvt_pk_bf16_f32 v34, v34, v35
	v_cvt_pk_bf16_f32 v35, v44, v45
	global_store_dwordx4 v41, v[32:35], s[90:91] sc1
	s_nop 1
	v_or_b32_e32 v32, v64, v96
	v_lshlrev_b32_e32 v38, 1, v32
	global_load_dwordx4 v[32:35], v38, s[90:91]
	s_waitcnt vmcnt(0)
	v_lshlrev_b32_e32 v36, 16, v32
	v_and_b32_e32 v37, 0xffff0000, v32
	v_lshlrev_b32_e32 v32, 16, v33
	v_and_b32_e32 v33, 0xffff0000, v33
	v_pk_add_f32 v[30:31], v[30:31], v[32:33]
	v_lshlrev_b32_e32 v32, 16, v34
	v_and_b32_e32 v33, 0xffff0000, v34
	v_lshlrev_b32_e32 v34, 16, v35
	v_and_b32_e32 v35, 0xffff0000, v35
	v_pk_add_f32 v[28:29], v[28:29], v[36:37]
	v_pk_add_f32 v[34:35], v[26:27], v[34:35]
	v_pk_add_f32 v[26:27], v[24:25], v[32:33]
	v_cvt_pk_bf16_f32 v24, v28, v29
	v_cvt_pk_bf16_f32 v25, v30, v31
	s_nop 0
	v_cvt_pk_bf16_f32 v26, v26, v27
	v_cvt_pk_bf16_f32 v27, v34, v35
	global_store_dwordx4 v38, v[24:27], s[90:91] sc1
	s_nop 1
	v_or_b32_e32 v24, v56, v96
	v_lshlrev_b32_e32 v30, 1, v24
	global_load_dwordx4 v[24:27], v30, s[90:91]
	s_waitcnt vmcnt(0)
	v_lshlrev_b32_e32 v28, 16, v24
	v_and_b32_e32 v29, 0xffff0000, v24
	v_lshlrev_b32_e32 v24, 16, v25
	v_and_b32_e32 v25, 0xffff0000, v25
	v_pk_add_f32 v[22:23], v[22:23], v[24:25]
	v_lshlrev_b32_e32 v24, 16, v26
	v_and_b32_e32 v25, 0xffff0000, v26
	v_lshlrev_b32_e32 v26, 16, v27
	v_and_b32_e32 v27, 0xffff0000, v27
	v_pk_add_f32 v[20:21], v[20:21], v[28:29]
	v_pk_add_f32 v[26:27], v[18:19], v[26:27]
	v_pk_add_f32 v[18:19], v[16:17], v[24:25]
	v_cvt_pk_bf16_f32 v16, v20, v21
	v_cvt_pk_bf16_f32 v17, v22, v23
	s_nop 0
	v_cvt_pk_bf16_f32 v18, v18, v19
	v_cvt_pk_bf16_f32 v19, v26, v27
	global_store_dwordx4 v30, v[16:19], s[90:91] sc1
	s_nop 1
	v_or_b32_e32 v16, v48, v96
	v_lshlrev_b32_e32 v22, 1, v16
	global_load_dwordx4 v[16:19], v22, s[90:91]
	s_waitcnt vmcnt(0)
	v_lshlrev_b32_e32 v20, 16, v16
	v_and_b32_e32 v21, 0xffff0000, v16
	v_lshlrev_b32_e32 v16, 16, v17
	v_and_b32_e32 v17, 0xffff0000, v17
	v_pk_add_f32 v[14:15], v[14:15], v[16:17]
	v_lshlrev_b32_e32 v16, 16, v18
	v_and_b32_e32 v17, 0xffff0000, v18
	v_lshlrev_b32_e32 v18, 16, v19
	v_and_b32_e32 v19, 0xffff0000, v19
	v_pk_add_f32 v[12:13], v[12:13], v[20:21]
	v_pk_add_f32 v[18:19], v[10:11], v[18:19]
	v_pk_add_f32 v[10:11], v[8:9], v[16:17]
	v_cvt_pk_bf16_f32 v8, v12, v13
	v_cvt_pk_bf16_f32 v9, v14, v15
	s_nop 0
	v_cvt_pk_bf16_f32 v10, v10, v11
	v_cvt_pk_bf16_f32 v11, v18, v19
	global_store_dwordx4 v22, v[8:11], s[90:91] sc1
	s_nop 1
	v_or_b32_e32 v8, v40, v96
	v_lshlrev_b32_e32 v14, 1, v8
	global_load_dwordx4 v[8:11], v14, s[90:91]
	s_waitcnt vmcnt(0)
	v_lshlrev_b32_e32 v12, 16, v8
	v_and_b32_e32 v13, 0xffff0000, v8
	v_lshlrev_b32_e32 v8, 16, v9
	v_and_b32_e32 v9, 0xffff0000, v9
	v_pk_add_f32 v[6:7], v[6:7], v[8:9]
	v_lshlrev_b32_e32 v8, 16, v10
	v_and_b32_e32 v9, 0xffff0000, v10
	v_lshlrev_b32_e32 v10, 16, v11
	v_and_b32_e32 v11, 0xffff0000, v11
	v_pk_add_f32 v[10:11], v[2:3], v[10:11]
	v_pk_add_f32 v[2:3], v[0:1], v[8:9]
	v_pk_add_f32 v[4:5], v[4:5], v[12:13]
	s_nop 0
	v_cvt_pk_bf16_f32 v0, v4, v5
	v_cvt_pk_bf16_f32 v1, v6, v7
	v_cvt_pk_bf16_f32 v2, v2, v3
	v_cvt_pk_bf16_f32 v3, v10, v11
	global_store_dwordx4 v14, v[0:3], s[90:91] sc1
	s_waitcnt vmcnt(0) lgkmcnt(0)
	s_barrier
	s_cbranch_scc0 .LBB0_162

; template <int N, int K, int EPI>
; __device__ __forceinline__ void gemm_phase(const bf16* __restrict__ A, const bf16* __restrict__ Bt, float* __restrict__ outf, bf16* __restrict__ outb,
;                            const float* __restrict__ ropec, const int W) {
;     ...
;       char* obase = (char*)(outb + (size_t)brow * N + bcol);
; #pragma unroll
;       for (int ai = 0; ai < 2; ++ai)
; #pragma unroll
;         for (int bj = 0; bj < 2; ++bj)
; #pragma unroll
;           for (int m = 0; m < 4; ++m) {
;             const unsigned lrow = ai * HALF + wr * 64 + m * 16 + efr;
;             const unsigned lcol = bj * HALF + wcb + efq * 8;
;             const f32x4 v0 = acc[ai][bj][m][0], v1 = acc[ai][bj][m][1];
;             if (EPI == EPI_RES) {
;               u32x4* d = (u32x4*)(obase + (size_t)((lrow * N + lcol) * 2u));
;               const u32x4 t = *d;
;               const f32x4 r0 = bf4_to_f32(u32x2{t[0], t[1]}) + v0, r1 = bf4_to_f32(u32x2{t[2], t[3]}) + v1;
;               u32x4 w = {cvtpk(r0[0], r0[1]), cvtpk(r0[2], r0[3]), cvtpk(r1[0], r1[1]), cvtpk(r1[2], r1[3])};
;               *d = w;
;     ...
;     asm volatile("s_waitcnt vmcnt(0) lgkmcnt(0)" ::: "memory");
;     __syncthreads();
.LBB0_208:
	v_mbcnt_lo_u32_b32 v133, -1, 0
	v_mbcnt_hi_u32_b32 v133, -1, v133
	s_lshl_b64 s[6:7], s[80:81], 11
	v_lshrrev_b32_e32 v132, 1, v133
	v_lshlrev_b32_e32 v133, 10, v133
	s_add_u32 s8, s66, s6
	v_and_b32_e32 v133, 0x3c00, v133
	s_addc_u32 s9, s67, s7
	s_lshl_b64 s[6:7], s[96:97], 1
	v_and_or_b32 v132, v132, 24, s4
	v_or_b32_e32 v133, s90, v133
	s_add_u32 s96, s8, s6
	v_or_b32_e32 v158, v133, v132
	s_addc_u32 s97, s9, s7
	v_lshlrev_b32_e32 v164, 1, v158
	global_load_dwordx4 v[158:161], v164, s[96:97]
	s_add_i32 s91, s91, s33
	s_cmpk_lt_i32 s91, 0x200
	s_waitcnt vmcnt(0)
	v_lshlrev_b32_e32 v162, 16, v158
	v_and_b32_e32 v163, 0xffff0000, v158
	v_lshlrev_b32_e32 v158, 16, v159
	v_and_b32_e32 v159, 0xffff0000, v159
	v_pk_add_f32 v[126:127], v[126:127], v[158:159]
	v_lshlrev_b32_e32 v158, 16, v160
	v_and_b32_e32 v159, 0xffff0000, v160
	v_lshlrev_b32_e32 v160, 16, v161
	v_and_b32_e32 v161, 0xffff0000, v161
	v_pk_add_f32 v[124:125], v[124:125], v[162:163]
	v_pk_add_f32 v[160:161], v[122:123], v[160:161]
	v_pk_add_f32 v[122:123], v[120:121], v[158:159]
	v_cvt_pk_bf16_f32 v120, v124, v125
	v_cvt_pk_bf16_f32 v121, v126, v127
	s_nop 0
	v_cvt_pk_bf16_f32 v122, v122, v123
	v_cvt_pk_bf16_f32 v123, v160, v161
	global_store_dwordx4 v164, v[120:123], s[96:97] sc1
	s_nop 1
	v_or_b32_e32 v120, 0x4000, v133
	v_or_b32_e32 v121, v120, v132
	v_lshlrev_b32_e32 v121, 1, v121
	global_load_dwordx4 v[122:125], v121, s[96:97]
	s_waitcnt vmcnt(0)
	v_lshlrev_b32_e32 v126, 16, v122
	v_and_b32_e32 v127, 0xffff0000, v122
	v_lshlrev_b32_e32 v122, 16, v123
	v_and_b32_e32 v123, 0xffff0000, v123
	v_pk_add_f32 v[118:119], v[118:119], v[122:123]
	v_lshlrev_b32_e32 v122, 16, v124
	v_and_b32_e32 v123, 0xffff0000, v124
	v_lshlrev_b32_e32 v124, 16, v125
	v_and_b32_e32 v125, 0xffff0000, v125
	v_pk_add_f32 v[116:117], v[116:117], v[126:127]
	v_pk_add_f32 v[124:125], v[114:115], v[124:125]
	v_pk_add_f32 v[114:115], v[112:113], v[122:123]
	v_cvt_pk_bf16_f32 v112, v116, v117
	v_cvt_pk_bf16_f32 v113, v118, v119
	s_nop 0
	v_cvt_pk_bf16_f32 v114, v114, v115
	v_cvt_pk_bf16_f32 v115, v124, v125
	global_store_dwordx4 v121, v[112:115], s[96:97] sc1
	s_nop 1
	v_or_b32_e32 v112, 0x8000, v133
	v_or_b32_e32 v113, v112, v132
	v_lshlrev_b32_e32 v113, 1, v113
	global_load_dwordx4 v[114:117], v113, s[96:97]
	s_waitcnt vmcnt(0)
	v_lshlrev_b32_e32 v118, 16, v114
	v_and_b32_e32 v119, 0xffff0000, v114
	v_lshlrev_b32_e32 v114, 16, v115
	v_and_b32_e32 v115, 0xffff0000, v115
	v_pk_add_f32 v[110:111], v[110:111], v[114:115]
	v_lshlrev_b32_e32 v114, 16, v116
	v_and_b32_e32 v115, 0xffff0000, v116
	v_lshlrev_b32_e32 v116, 16, v117
	v_and_b32_e32 v117, 0xffff0000, v117
	v_pk_add_f32 v[108:109], v[108:109], v[118:119]
	v_pk_add_f32 v[116:117], v[106:107], v[116:117]
	v_pk_add_f32 v[106:107], v[104:105], v[114:115]
	v_cvt_pk_bf16_f32 v104, v108, v109
	v_cvt_pk_bf16_f32 v105, v110, v111
	s_nop 0
	v_cvt_pk_bf16_f32 v106, v106, v107
	v_cvt_pk_bf16_f32 v107, v116, v117
	global_store_dwordx4 v113, v[104:107], s[96:97] sc1
	s_nop 1
	v_or_b32_e32 v104, 0xc000, v133
	v_or_b32_e32 v105, v104, v132
	v_lshlrev_b32_e32 v105, 1, v105
	global_load_dwordx4 v[106:109], v105, s[96:97]
	s_waitcnt vmcnt(0)
	v_lshlrev_b32_e32 v110, 16, v106
	v_and_b32_e32 v111, 0xffff0000, v106
	v_lshlrev_b32_e32 v106, 16, v107
	v_and_b32_e32 v107, 0xffff0000, v107
	v_pk_add_f32 v[102:103], v[102:103], v[106:107]
	v_lshlrev_b32_e32 v106, 16, v108
	v_and_b32_e32 v107, 0xffff0000, v108
	v_lshlrev_b32_e32 v108, 16, v109
	v_and_b32_e32 v109, 0xffff0000, v109
	v_pk_add_f32 v[100:101], v[100:101], v[110:111]
	v_pk_add_f32 v[108:109], v[98:99], v[108:109]
	v_pk_add_f32 v[98:99], v[96:97], v[106:107]
	v_cvt_pk_bf16_f32 v96, v100, v101
	v_cvt_pk_bf16_f32 v97, v102, v103
	s_nop 0
	v_cvt_pk_bf16_f32 v98, v98, v99
	v_cvt_pk_bf16_f32 v99, v108, v109
	global_store_dwordx4 v105, v[96:99], s[96:97] sc1
	s_nop 1
	v_or_b32_e32 v96, 0x80, v132
	v_or_b32_e32 v97, v96, v133
	v_lshlrev_b32_e32 v97, 1, v97
	global_load_dwordx4 v[98:101], v97, s[96:97]
	s_waitcnt vmcnt(0)
	v_lshlrev_b32_e32 v102, 16, v98
	v_and_b32_e32 v103, 0xffff0000, v98
	v_lshlrev_b32_e32 v98, 16, v99
	v_and_b32_e32 v99, 0xffff0000, v99
	v_pk_add_f32 v[94:95], v[94:95], v[98:99]
	v_lshlrev_b32_e32 v98, 16, v100
	v_and_b32_e32 v99, 0xffff0000, v100
	v_lshlrev_b32_e32 v100, 16, v101
	v_and_b32_e32 v101, 0xffff0000, v101
	v_pk_add_f32 v[92:93], v[92:93], v[102:103]
	v_pk_add_f32 v[100:101], v[90:91], v[100:101]
	v_pk_add_f32 v[90:91], v[88:89], v[98:99]
	v_cvt_pk_bf16_f32 v88, v92, v93
	v_cvt_pk_bf16_f32 v89, v94, v95
	s_nop 0
	v_cvt_pk_bf16_f32 v90, v90, v91
	v_cvt_pk_bf16_f32 v91, v100, v101
	global_store_dwordx4 v97, v[88:91], s[96:97] sc1
	s_nop 1
	v_or_b32_e32 v88, v120, v96
	v_lshlrev_b32_e32 v94, 1, v88
	global_load_dwordx4 v[88:91], v94, s[96:97]
	s_waitcnt vmcnt(0)
	v_lshlrev_b32_e32 v92, 16, v88
	v_and_b32_e32 v93, 0xffff0000, v88
	v_lshlrev_b32_e32 v88, 16, v89
	v_and_b32_e32 v89, 0xffff0000, v89
	v_pk_add_f32 v[86:87], v[86:87], v[88:89]
	v_lshlrev_b32_e32 v88, 16, v90
	v_and_b32_e32 v89, 0xffff0000, v90
	v_lshlrev_b32_e32 v90, 16, v91
	v_and_b32_e32 v91, 0xffff0000, v91
	v_pk_add_f32 v[84:85], v[84:85], v[92:93]
	v_pk_add_f32 v[90:91], v[82:83], v[90:91]
	v_pk_add_f32 v[82:83], v[80:81], v[88:89]
	v_cvt_pk_bf16_f32 v80, v84, v85
	v_cvt_pk_bf16_f32 v81, v86, v87
	s_nop 0
	v_cvt_pk_bf16_f32 v82, v82, v83
	v_cvt_pk_bf16_f32 v83, v90, v91
	global_store_dwordx4 v94, v[80:83], s[96:97] sc1
	s_nop 1
	v_or_b32_e32 v80, v112, v96
	v_lshlrev_b32_e32 v86, 1, v80
	global_load_dwordx4 v[80:83], v86, s[96:97]
	s_waitcnt vmcnt(0)
; template <int N, int K, int EPI>
; __device__ __forceinline__ void gemm_phase(const bf16* __restrict__ A, const bf16* __restrict__ Bt, float* __restrict__ outf, bf16* __restrict__ outb,
;                            const float* __restrict__ ropec, const int W) {
;     ...
;       char* obase = (char*)(outb + (size_t)brow * N + bcol);
; #pragma unroll
;       for (int ai = 0; ai < 2; ++ai)
; #pragma unroll
;         for (int bj = 0; bj < 2; ++bj)
; #pragma unroll
;           for (int m = 0; m < 4; ++m) {
;             const unsigned lrow = ai * HALF + wr * 64 + m * 16 + efr;
;             const unsigned lcol = bj * HALF + wcb + efq * 8;
;             const f32x4 v0 = acc[ai][bj][m][0], v1 = acc[ai][bj][m][1];
;             if (EPI == EPI_RES) {
;               u32x4* d = (u32x4*)(obase + (size_t)((lrow * N + lcol) * 2u));
;               const u32x4 t = *d;
;               const f32x4 r0 = bf4_to_f32(u32x2{t[0], t[1]}) + v0, r1 = bf4_to_f32(u32x2{t[2], t[3]}) + v1;
;               u32x4 w = {cvtpk(r0[0], r0[1]), cvtpk(r0[2], r0[3]), cvtpk(r1[0], r1[1]), cvtpk(r1[2], r1[3])};
;               *d = w;
	v_lshlrev_b32_e32 v84, 16, v80
	v_and_b32_e32 v85, 0xffff0000, v80
	v_lshlrev_b32_e32 v80, 16, v81
	v_and_b32_e32 v81, 0xffff0000, v81
	v_pk_add_f32 v[78:79], v[78:79], v[80:81]
	v_lshlrev_b32_e32 v80, 16, v82
	v_and_b32_e32 v81, 0xffff0000, v82
	v_lshlrev_b32_e32 v82, 16, v83
	v_and_b32_e32 v83, 0xffff0000, v83
	v_pk_add_f32 v[76:77], v[76:77], v[84:85]
	v_pk_add_f32 v[82:83], v[74:75], v[82:83]
	v_pk_add_f32 v[74:75], v[72:73], v[80:81]
	v_cvt_pk_bf16_f32 v72, v76, v77
	v_cvt_pk_bf16_f32 v73, v78, v79
	s_nop 0
	v_cvt_pk_bf16_f32 v74, v74, v75
	v_cvt_pk_bf16_f32 v75, v82, v83
	global_store_dwordx4 v86, v[72:75], s[96:97] sc1
	s_nop 1
	v_or_b32_e32 v72, v104, v96
	v_lshlrev_b32_e32 v78, 1, v72
	global_load_dwordx4 v[72:75], v78, s[96:97]
	s_waitcnt vmcnt(0)
	v_lshlrev_b32_e32 v76, 16, v72
	v_and_b32_e32 v77, 0xffff0000, v72
	v_lshlrev_b32_e32 v72, 16, v73
	v_and_b32_e32 v73, 0xffff0000, v73
	v_pk_add_f32 v[70:71], v[70:71], v[72:73]
	v_lshlrev_b32_e32 v72, 16, v74
	v_and_b32_e32 v73, 0xffff0000, v74
	v_lshlrev_b32_e32 v74, 16, v75
	v_and_b32_e32 v75, 0xffff0000, v75
	v_pk_add_f32 v[68:69], v[68:69], v[76:77]
	v_pk_add_f32 v[74:75], v[66:67], v[74:75]
	v_pk_add_f32 v[66:67], v[64:65], v[72:73]
	v_cvt_pk_bf16_f32 v64, v68, v69
	v_cvt_pk_bf16_f32 v65, v70, v71
	s_nop 0
	v_cvt_pk_bf16_f32 v66, v66, v67
	v_cvt_pk_bf16_f32 v67, v74, v75
	global_store_dwordx4 v78, v[64:67], s[96:97] sc1
	s_nop 1
	v_add_u32_e32 v64, 0x20000, v133
	v_or_b32_e32 v65, v64, v132
	v_lshlrev_b32_e32 v65, 1, v65
	global_load_dwordx4 v[66:69], v65, s[96:97]
	s_waitcnt vmcnt(0)
	v_lshlrev_b32_e32 v70, 16, v66
	v_and_b32_e32 v71, 0xffff0000, v66
	v_lshlrev_b32_e32 v66, 16, v67
	v_and_b32_e32 v67, 0xffff0000, v67
	v_pk_add_f32 v[62:63], v[62:63], v[66:67]
	v_lshlrev_b32_e32 v66, 16, v68
	v_and_b32_e32 v67, 0xffff0000, v68
	v_lshlrev_b32_e32 v68, 16, v69
	v_and_b32_e32 v69, 0xffff0000, v69
	v_pk_add_f32 v[60:61], v[60:61], v[70:71]
	v_pk_add_f32 v[68:69], v[58:59], v[68:69]
	v_pk_add_f32 v[58:59], v[56:57], v[66:67]
	v_cvt_pk_bf16_f32 v56, v60, v61
	v_cvt_pk_bf16_f32 v57, v62, v63
	s_nop 0
	v_cvt_pk_bf16_f32 v58, v58, v59
	v_cvt_pk_bf16_f32 v59, v68, v69
	global_store_dwordx4 v65, v[56:59], s[96:97] sc1
	s_nop 1
	v_add_u32_e32 v56, 0x24000, v133
	v_or_b32_e32 v57, v56, v132
	v_lshlrev_b32_e32 v57, 1, v57
	global_load_dwordx4 v[58:61], v57, s[96:97]
	s_waitcnt vmcnt(0)
	v_lshlrev_b32_e32 v62, 16, v58
	v_and_b32_e32 v63, 0xffff0000, v58
	v_lshlrev_b32_e32 v58, 16, v59
	v_and_b32_e32 v59, 0xffff0000, v59
	v_pk_add_f32 v[54:55], v[54:55], v[58:59]
	v_lshlrev_b32_e32 v58, 16, v60
	v_and_b32_e32 v59, 0xffff0000, v60
	v_lshlrev_b32_e32 v60, 16, v61
	v_and_b32_e32 v61, 0xffff0000, v61
	v_pk_add_f32 v[52:53], v[52:53], v[62:63]
	v_pk_add_f32 v[60:61], v[50:51], v[60:61]
	v_pk_add_f32 v[50:51], v[48:49], v[58:59]
	v_cvt_pk_bf16_f32 v48, v52, v53
	v_cvt_pk_bf16_f32 v49, v54, v55
	s_nop 0
	v_cvt_pk_bf16_f32 v50, v50, v51
	v_cvt_pk_bf16_f32 v51, v60, v61
	global_store_dwordx4 v57, v[48:51], s[96:97] sc1
	s_nop 1
	v_add_u32_e32 v48, 0x28000, v133
	v_or_b32_e32 v49, v48, v132
	v_lshlrev_b32_e32 v49, 1, v49
	global_load_dwordx4 v[50:53], v49, s[96:97]
	s_waitcnt vmcnt(0)
	v_lshlrev_b32_e32 v54, 16, v50
	v_and_b32_e32 v55, 0xffff0000, v50
	v_lshlrev_b32_e32 v50, 16, v51
	v_and_b32_e32 v51, 0xffff0000, v51
	v_pk_add_f32 v[46:47], v[46:47], v[50:51]
	v_lshlrev_b32_e32 v50, 16, v52
	v_and_b32_e32 v51, 0xffff0000, v52
	v_lshlrev_b32_e32 v52, 16, v53
	v_and_b32_e32 v53, 0xffff0000, v53
	v_pk_add_f32 v[44:45], v[44:45], v[54:55]
	v_pk_add_f32 v[52:53], v[42:43], v[52:53]
	v_pk_add_f32 v[42:43], v[40:41], v[50:51]
	v_cvt_pk_bf16_f32 v40, v44, v45
	v_cvt_pk_bf16_f32 v41, v46, v47
	s_nop 0
	v_cvt_pk_bf16_f32 v42, v42, v43
	v_cvt_pk_bf16_f32 v43, v52, v53
	global_store_dwordx4 v49, v[40:43], s[96:97] sc1
	s_nop 1
	v_add_u32_e32 v40, 0x2c000, v133
	v_or_b32_e32 v41, v40, v132
	v_lshlrev_b32_e32 v41, 1, v41
	global_load_dwordx4 v[42:45], v41, s[96:97]
	s_waitcnt vmcnt(0)
; template <int N, int K, int EPI>
; __device__ __forceinline__ void gemm_phase(const bf16* __restrict__ A, const bf16* __restrict__ Bt, float* __restrict__ outf, bf16* __restrict__ outb,
;                            const float* __restrict__ ropec, const int W) {
;     ...
;       char* obase = (char*)(outb + (size_t)brow * N + bcol);
; #pragma unroll
;       for (int ai = 0; ai < 2; ++ai)
; #pragma unroll
;         for (int bj = 0; bj < 2; ++bj)
; #pragma unroll
;           for (int m = 0; m < 4; ++m) {
;             const unsigned lrow = ai * HALF + wr * 64 + m * 16 + efr;
;             const unsigned lcol = bj * HALF + wcb + efq * 8;
;             const f32x4 v0 = acc[ai][bj][m][0], v1 = acc[ai][bj][m][1];
;             if (EPI == EPI_RES) {
;               u32x4* d = (u32x4*)(obase + (size_t)((lrow * N + lcol) * 2u));
;               const u32x4 t = *d;
;               const f32x4 r0 = bf4_to_f32(u32x2{t[0], t[1]}) + v0, r1 = bf4_to_f32(u32x2{t[2], t[3]}) + v1;
;               u32x4 w = {cvtpk(r0[0], r0[1]), cvtpk(r0[2], r0[3]), cvtpk(r1[0], r1[1]), cvtpk(r1[2], r1[3])};
;               *d = w;
;             } else {
;               const float a0 = fmaxf(v0[0], 0.f), a1 = fmaxf(v0[1], 0.f), a2 = fmaxf(v0[2], 0.f), a3 = fmaxf(v0[3], 0.f);
;               const float b0 = fmaxf(v1[0], 0.f), b1 = fmaxf(v1[1], 0.f), b2 = fmaxf(v1[2], 0.f), b3 = fmaxf(v1[3], 0.f);
;               u32x4 w = {cvtpk(a0 * a0, a1 * a1), cvtpk(a2 * a2, a3 * a3), cvtpk(b0 * b0, b1 * b1), cvtpk(b2 * b2, b3 * b3)};
;               *(u32x4*)(obase + (size_t)((lrow * N + lcol) * 2u)) = w;
;             }
;           }
;     }
;     asm volatile("s_waitcnt vmcnt(0) lgkmcnt(0)" ::: "memory");
;     __syncthreads();
	v_lshlrev_b32_e32 v46, 16, v42
	v_and_b32_e32 v47, 0xffff0000, v42
	v_lshlrev_b32_e32 v42, 16, v43
	v_and_b32_e32 v43, 0xffff0000, v43
	v_pk_add_f32 v[38:39], v[38:39], v[42:43]
	v_lshlrev_b32_e32 v42, 16, v44
	v_and_b32_e32 v43, 0xffff0000, v44
	v_lshlrev_b32_e32 v44, 16, v45
	v_and_b32_e32 v45, 0xffff0000, v45
	v_pk_add_f32 v[36:37], v[36:37], v[46:47]
	v_pk_add_f32 v[44:45], v[34:35], v[44:45]
	v_pk_add_f32 v[34:35], v[32:33], v[42:43]
	v_cvt_pk_bf16_f32 v32, v36, v37
	v_cvt_pk_bf16_f32 v33, v38, v39
	s_nop 0
	v_cvt_pk_bf16_f32 v34, v34, v35
	v_cvt_pk_bf16_f32 v35, v44, v45
	global_store_dwordx4 v41, v[32:35], s[96:97] sc1
	s_nop 1
	v_or_b32_e32 v32, v64, v96
	v_lshlrev_b32_e32 v38, 1, v32
	global_load_dwordx4 v[32:35], v38, s[96:97]
	s_waitcnt vmcnt(0)
	v_lshlrev_b32_e32 v36, 16, v32
	v_and_b32_e32 v37, 0xffff0000, v32
	v_lshlrev_b32_e32 v32, 16, v33
	v_and_b32_e32 v33, 0xffff0000, v33
	v_pk_add_f32 v[30:31], v[30:31], v[32:33]
	v_lshlrev_b32_e32 v32, 16, v34
	v_and_b32_e32 v33, 0xffff0000, v34
	v_lshlrev_b32_e32 v34, 16, v35
	v_and_b32_e32 v35, 0xffff0000, v35
	v_pk_add_f32 v[28:29], v[28:29], v[36:37]
	v_pk_add_f32 v[34:35], v[26:27], v[34:35]
	v_pk_add_f32 v[26:27], v[24:25], v[32:33]
	v_cvt_pk_bf16_f32 v24, v28, v29
	v_cvt_pk_bf16_f32 v25, v30, v31
	s_nop 0
	v_cvt_pk_bf16_f32 v26, v26, v27
	v_cvt_pk_bf16_f32 v27, v34, v35
	global_store_dwordx4 v38, v[24:27], s[96:97] sc1
	s_nop 1
	v_or_b32_e32 v24, v56, v96
	v_lshlrev_b32_e32 v30, 1, v24
	global_load_dwordx4 v[24:27], v30, s[96:97]
	s_waitcnt vmcnt(0)
	v_lshlrev_b32_e32 v28, 16, v24
	v_and_b32_e32 v29, 0xffff0000, v24
	v_lshlrev_b32_e32 v24, 16, v25
	v_and_b32_e32 v25, 0xffff0000, v25
	v_pk_add_f32 v[22:23], v[22:23], v[24:25]
	v_lshlrev_b32_e32 v24, 16, v26
	v_and_b32_e32 v25, 0xffff0000, v26
	v_lshlrev_b32_e32 v26, 16, v27
	v_and_b32_e32 v27, 0xffff0000, v27
	v_pk_add_f32 v[20:21], v[20:21], v[28:29]
	v_pk_add_f32 v[26:27], v[18:19], v[26:27]
	v_pk_add_f32 v[18:19], v[16:17], v[24:25]
	v_cvt_pk_bf16_f32 v16, v20, v21
	v_cvt_pk_bf16_f32 v17, v22, v23
	s_nop 0
	v_cvt_pk_bf16_f32 v18, v18, v19
	v_cvt_pk_bf16_f32 v19, v26, v27
	global_store_dwordx4 v30, v[16:19], s[96:97] sc1
	s_nop 1
	v_or_b32_e32 v16, v48, v96
	v_lshlrev_b32_e32 v22, 1, v16
	global_load_dwordx4 v[16:19], v22, s[96:97]
	s_waitcnt vmcnt(0)
	v_lshlrev_b32_e32 v20, 16, v16
	v_and_b32_e32 v21, 0xffff0000, v16
	v_lshlrev_b32_e32 v16, 16, v17
	v_and_b32_e32 v17, 0xffff0000, v17
	v_pk_add_f32 v[14:15], v[14:15], v[16:17]
	v_lshlrev_b32_e32 v16, 16, v18
	v_and_b32_e32 v17, 0xffff0000, v18
	v_lshlrev_b32_e32 v18, 16, v19
	v_and_b32_e32 v19, 0xffff0000, v19
	v_pk_add_f32 v[12:13], v[12:13], v[20:21]
	v_pk_add_f32 v[18:19], v[10:11], v[18:19]
	v_pk_add_f32 v[10:11], v[8:9], v[16:17]
	v_cvt_pk_bf16_f32 v8, v12, v13
	v_cvt_pk_bf16_f32 v9, v14, v15
	s_nop 0
	v_cvt_pk_bf16_f32 v10, v10, v11
	v_cvt_pk_bf16_f32 v11, v18, v19
	global_store_dwordx4 v22, v[8:11], s[96:97] sc1
	s_nop 1
	v_or_b32_e32 v8, v40, v96
	v_lshlrev_b32_e32 v14, 1, v8
	global_load_dwordx4 v[8:11], v14, s[96:97]
	s_waitcnt vmcnt(0)
	v_lshlrev_b32_e32 v12, 16, v8
	v_and_b32_e32 v13, 0xffff0000, v8
	v_lshlrev_b32_e32 v8, 16, v9
	v_and_b32_e32 v9, 0xffff0000, v9
	v_pk_add_f32 v[6:7], v[6:7], v[8:9]
	v_lshlrev_b32_e32 v8, 16, v10
	v_and_b32_e32 v9, 0xffff0000, v10
	v_lshlrev_b32_e32 v10, 16, v11
	v_and_b32_e32 v11, 0xffff0000, v11
	v_pk_add_f32 v[10:11], v[2:3], v[10:11]
	v_pk_add_f32 v[2:3], v[0:1], v[8:9]
	v_pk_add_f32 v[4:5], v[4:5], v[12:13]
	s_nop 0
	v_cvt_pk_bf16_f32 v0, v4, v5
	v_cvt_pk_bf16_f32 v1, v6, v7
	v_cvt_pk_bf16_f32 v2, v2, v3
	v_cvt_pk_bf16_f32 v3, v10, v11
	global_store_dwordx4 v14, v[0:3], s[96:97] sc1
	s_waitcnt vmcnt(0) lgkmcnt(0)
	s_barrier
	s_cbranch_scc0 .LBB0_219

; template <int N, int K, int EPI>
; __device__ __forceinline__ void gemm_phase(const bf16* __restrict__ A, const bf16* __restrict__ Bt, float* __restrict__ outf, bf16* __restrict__ outb,
;                            const float* __restrict__ ropec, const int W) {
;     ...
;       char* obase = (char*)(outb + (size_t)brow * N + bcol);
; #pragma unroll
;       for (int ai = 0; ai < 2; ++ai)
; #pragma unroll
;         for (int bj = 0; bj < 2; ++bj)
; #pragma unroll
;           for (int m = 0; m < 4; ++m) {
;             const unsigned lrow = ai * HALF + wr * 64 + m * 16 + efr;
;             const unsigned lcol = bj * HALF + wcb + efq * 8;
;             const f32x4 v0 = acc[ai][bj][m][0], v1 = acc[ai][bj][m][1];
;             if (EPI == EPI_RES) {
;               u32x4* d = (u32x4*)(obase + (size_t)((lrow * N + lcol) * 2u));
;               const u32x4 t = *d;
;               const f32x4 r0 = bf4_to_f32(u32x2{t[0], t[1]}) + v0, r1 = bf4_to_f32(u32x2{t[2], t[3]}) + v1;
;               u32x4 w = {cvtpk(r0[0], r0[1]), cvtpk(r0[2], r0[3]), cvtpk(r1[0], r1[1]), cvtpk(r1[2], r1[3])};
;               *d = w;
.LBB0_361:
	v_mbcnt_lo_u32_b32 v133, -1, 0
	v_mbcnt_hi_u32_b32 v133, -1, v133
	s_lshl_b64 s[8:9], s[76:77], 1
	v_lshrrev_b32_e32 v132, 1, v133
	v_lshlrev_b32_e32 v133, 10, v133
	s_add_u32 s76, s66, s8
	v_and_b32_e32 v133, 0x3c00, v133
	s_addc_u32 s77, s67, s9
	s_lshl_b64 s[8:9], s[74:75], 1
	v_and_or_b32 v132, v132, 24, s4
	v_or_b32_e32 v133, s55, v133
	s_add_u32 s74, s76, s8
	v_or_b32_e32 v158, v133, v132
	s_addc_u32 s75, s77, s9
	v_lshlrev_b32_e32 v166, 1, v158
	global_load_dwordx4 v[158:161], v166, s[74:75]
	v_or_b32_e32 v167, 0x4000, v133
	v_or_b32_e32 v162, v167, v132
	v_lshlrev_b32_e32 v168, 1, v162
	s_add_i32 s59, s59, s33
	s_cmpk_lt_i32 s59, 0x200
	s_waitcnt vmcnt(0)
	v_lshlrev_b32_e32 v162, 16, v158
	v_and_b32_e32 v163, 0xffff0000, v158
	v_lshlrev_b32_e32 v158, 16, v159
	v_and_b32_e32 v159, 0xffff0000, v159
	v_lshlrev_b32_e32 v164, 16, v160
	v_and_b32_e32 v165, 0xffff0000, v160
	v_lshlrev_b32_e32 v160, 16, v161
	v_and_b32_e32 v161, 0xffff0000, v161
	v_pk_add_f32 v[122:123], v[122:123], v[158:159]
	v_pk_add_f32 v[120:121], v[120:121], v[162:163]
	v_pk_add_f32 v[126:127], v[126:127], v[160:161]
	v_pk_add_f32 v[124:125], v[124:125], v[164:165]
	v_cvt_pk_bf16_f32 v120, v120, v121
	v_cvt_pk_bf16_f32 v121, v122, v123
	v_or_b32_e32 v158, 0x8000, v133
	v_cvt_pk_bf16_f32 v122, v124, v125
	v_cvt_pk_bf16_f32 v123, v126, v127
	global_store_dwordx4 v166, v[120:123], s[74:75] sc1
	global_load_dwordx4 v[120:123], v168, s[74:75]
	v_or_b32_e32 v124, v158, v132
	v_lshlrev_b32_e32 v159, 1, v124
	s_waitcnt vmcnt(0)
	v_lshlrev_b32_e32 v124, 16, v120
	v_and_b32_e32 v125, 0xffff0000, v120
	v_lshlrev_b32_e32 v120, 16, v121
	v_and_b32_e32 v121, 0xffff0000, v121
	v_lshlrev_b32_e32 v126, 16, v122
	v_and_b32_e32 v127, 0xffff0000, v122
	v_lshlrev_b32_e32 v122, 16, v123
	v_and_b32_e32 v123, 0xffff0000, v123
	v_pk_add_f32 v[114:115], v[114:115], v[120:121]
	v_pk_add_f32 v[112:113], v[112:113], v[124:125]
	v_pk_add_f32 v[118:119], v[118:119], v[122:123]
	v_pk_add_f32 v[116:117], v[116:117], v[126:127]
	v_cvt_pk_bf16_f32 v112, v112, v113
	v_cvt_pk_bf16_f32 v113, v114, v115
	v_or_b32_e32 v120, 0xc000, v133
	v_cvt_pk_bf16_f32 v114, v116, v117
	v_cvt_pk_bf16_f32 v115, v118, v119
	global_store_dwordx4 v168, v[112:115], s[74:75] sc1
	global_load_dwordx4 v[112:115], v159, s[74:75]
	v_or_b32_e32 v116, v120, v132
	v_lshlrev_b32_e32 v121, 1, v116
	s_waitcnt vmcnt(0)
	v_lshlrev_b32_e32 v116, 16, v112
	v_and_b32_e32 v117, 0xffff0000, v112
	v_lshlrev_b32_e32 v112, 16, v113
	v_and_b32_e32 v113, 0xffff0000, v113
	v_lshlrev_b32_e32 v118, 16, v114
	v_and_b32_e32 v119, 0xffff0000, v114
	v_lshlrev_b32_e32 v114, 16, v115
	v_and_b32_e32 v115, 0xffff0000, v115
	v_pk_add_f32 v[106:107], v[106:107], v[112:113]
	v_pk_add_f32 v[104:105], v[104:105], v[116:117]
	v_pk_add_f32 v[110:111], v[110:111], v[114:115]
	v_pk_add_f32 v[108:109], v[108:109], v[118:119]
	v_cvt_pk_bf16_f32 v104, v104, v105
	v_cvt_pk_bf16_f32 v105, v106, v107
	s_nop 0
	v_cvt_pk_bf16_f32 v106, v108, v109
	v_cvt_pk_bf16_f32 v107, v110, v111
	global_store_dwordx4 v159, v[104:107], s[74:75] sc1
	global_load_dwordx4 v[106:109], v121, s[74:75]
	s_waitcnt vmcnt(0)
	v_lshlrev_b32_e32 v110, 16, v106
	v_or_b32_e32 v104, 0x80, v132
	v_and_b32_e32 v111, 0xffff0000, v106
	v_lshlrev_b32_e32 v106, 16, v107
	v_and_b32_e32 v107, 0xffff0000, v107
	v_or_b32_e32 v105, v104, v133
	v_lshlrev_b32_e32 v112, 16, v108
	v_and_b32_e32 v113, 0xffff0000, v108
	v_lshlrev_b32_e32 v108, 16, v109
	v_and_b32_e32 v109, 0xffff0000, v109
	v_pk_add_f32 v[98:99], v[98:99], v[106:107]
	v_pk_add_f32 v[96:97], v[96:97], v[110:111]
	v_lshlrev_b32_e32 v105, 1, v105
	v_pk_add_f32 v[102:103], v[102:103], v[108:109]
	v_pk_add_f32 v[100:101], v[100:101], v[112:113]
	v_cvt_pk_bf16_f32 v96, v96, v97
	v_cvt_pk_bf16_f32 v97, v98, v99
	s_nop 0
	v_cvt_pk_bf16_f32 v98, v100, v101
	v_cvt_pk_bf16_f32 v99, v102, v103
	global_store_dwordx4 v121, v[96:99], s[74:75] sc1
	global_load_dwordx4 v[96:99], v105, s[74:75]
	v_or_b32_e32 v100, v167, v104
	v_lshlrev_b32_e32 v106, 1, v100
	s_waitcnt vmcnt(0)
	v_lshlrev_b32_e32 v100, 16, v96
	v_and_b32_e32 v101, 0xffff0000, v96
	v_lshlrev_b32_e32 v96, 16, v97
	v_and_b32_e32 v97, 0xffff0000, v97
	v_lshlrev_b32_e32 v102, 16, v98
	v_and_b32_e32 v103, 0xffff0000, v98
	v_lshlrev_b32_e32 v98, 16, v99
	v_and_b32_e32 v99, 0xffff0000, v99
	v_pk_add_f32 v[90:91], v[90:91], v[96:97]
	v_pk_add_f32 v[88:89], v[88:89], v[100:101]
	v_pk_add_f32 v[94:95], v[94:95], v[98:99]
	v_pk_add_f32 v[92:93], v[92:93], v[102:103]
	v_cvt_pk_bf16_f32 v88, v88, v89
	v_cvt_pk_bf16_f32 v89, v90, v91
	s_nop 0
	v_cvt_pk_bf16_f32 v90, v92, v93
	v_cvt_pk_bf16_f32 v91, v94, v95
	global_store_dwordx4 v105, v[88:91], s[74:75] sc1
	global_load_dwordx4 v[88:91], v106, s[74:75]
	v_or_b32_e32 v92, v158, v104
	v_lshlrev_b32_e32 v96, 1, v92
	s_waitcnt vmcnt(0)
	v_lshlrev_b32_e32 v92, 16, v88
	v_and_b32_e32 v93, 0xffff0000, v88
	v_lshlrev_b32_e32 v88, 16, v89
	v_and_b32_e32 v89, 0xffff0000, v89
	v_lshlrev_b32_e32 v94, 16, v90
	v_and_b32_e32 v95, 0xffff0000, v90
	v_lshlrev_b32_e32 v90, 16, v91
	v_and_b32_e32 v91, 0xffff0000, v91
	v_pk_add_f32 v[82:83], v[82:83], v[88:89]
	v_pk_add_f32 v[80:81], v[80:81], v[92:93]
	v_pk_add_f32 v[86:87], v[86:87], v[90:91]
	v_pk_add_f32 v[84:85], v[84:85], v[94:95]
	v_cvt_pk_bf16_f32 v80, v80, v81
	v_cvt_pk_bf16_f32 v81, v82, v83
	s_nop 0
	v_cvt_pk_bf16_f32 v82, v84, v85
	v_cvt_pk_bf16_f32 v83, v86, v87
	global_store_dwordx4 v106, v[80:83], s[74:75] sc1
	global_load_dwordx4 v[80:83], v96, s[74:75]
	v_or_b32_e32 v84, v120, v104
	v_lshlrev_b32_e32 v88, 1, v84
	s_waitcnt vmcnt(0)
; template <int N, int K, int EPI>
; __device__ __forceinline__ void gemm_phase(const bf16* __restrict__ A, const bf16* __restrict__ Bt, float* __restrict__ outf, bf16* __restrict__ outb,
;                            const float* __restrict__ ropec, const int W) {
;     ...
;             const f32x4 v0 = acc[ai][bj][m][0], v1 = acc[ai][bj][m][1];
;             if (EPI == EPI_RES) {
;               u32x4* d = (u32x4*)(obase + (size_t)((lrow * N + lcol) * 2u));
;               const u32x4 t = *d;
;               const f32x4 r0 = bf4_to_f32(u32x2{t[0], t[1]}) + v0, r1 = bf4_to_f32(u32x2{t[2], t[3]}) + v1;
;               u32x4 w = {cvtpk(r0[0], r0[1]), cvtpk(r0[2], r0[3]), cvtpk(r1[0], r1[1]), cvtpk(r1[2], r1[3])};
;               *d = w;
	v_lshlrev_b32_e32 v84, 16, v80
	v_and_b32_e32 v85, 0xffff0000, v80
	v_lshlrev_b32_e32 v80, 16, v81
	v_and_b32_e32 v81, 0xffff0000, v81
	v_lshlrev_b32_e32 v86, 16, v82
	v_and_b32_e32 v87, 0xffff0000, v82
	v_lshlrev_b32_e32 v82, 16, v83
	v_and_b32_e32 v83, 0xffff0000, v83
	v_pk_add_f32 v[74:75], v[74:75], v[80:81]
	v_pk_add_f32 v[72:73], v[72:73], v[84:85]
	v_pk_add_f32 v[78:79], v[78:79], v[82:83]
	v_pk_add_f32 v[76:77], v[76:77], v[86:87]
	v_cvt_pk_bf16_f32 v72, v72, v73
	v_cvt_pk_bf16_f32 v73, v74, v75
	v_add_u32_e32 v80, 0x20000, v133
	v_cvt_pk_bf16_f32 v74, v76, v77
	v_cvt_pk_bf16_f32 v75, v78, v79
	global_store_dwordx4 v96, v[72:75], s[74:75] sc1
	global_load_dwordx4 v[72:75], v88, s[74:75]
	v_or_b32_e32 v76, v80, v132
	v_lshlrev_b32_e32 v81, 1, v76
	s_waitcnt vmcnt(0)
	v_lshlrev_b32_e32 v76, 16, v72
	v_and_b32_e32 v77, 0xffff0000, v72
	v_lshlrev_b32_e32 v72, 16, v73
	v_and_b32_e32 v73, 0xffff0000, v73
	v_lshlrev_b32_e32 v78, 16, v74
	v_and_b32_e32 v79, 0xffff0000, v74
	v_lshlrev_b32_e32 v74, 16, v75
	v_and_b32_e32 v75, 0xffff0000, v75
	v_pk_add_f32 v[66:67], v[66:67], v[72:73]
	v_pk_add_f32 v[64:65], v[64:65], v[76:77]
	v_pk_add_f32 v[70:71], v[70:71], v[74:75]
	v_pk_add_f32 v[68:69], v[68:69], v[78:79]
	v_cvt_pk_bf16_f32 v64, v64, v65
	v_cvt_pk_bf16_f32 v65, v66, v67
	v_add_u32_e32 v72, 0x24000, v133
	v_cvt_pk_bf16_f32 v66, v68, v69
	v_cvt_pk_bf16_f32 v67, v70, v71
	global_store_dwordx4 v88, v[64:67], s[74:75] sc1
	global_load_dwordx4 v[64:67], v81, s[74:75]
	v_or_b32_e32 v68, v72, v132
	v_lshlrev_b32_e32 v73, 1, v68
	s_waitcnt vmcnt(0)
	v_lshlrev_b32_e32 v68, 16, v64
	v_and_b32_e32 v69, 0xffff0000, v64
	v_lshlrev_b32_e32 v64, 16, v65
	v_and_b32_e32 v65, 0xffff0000, v65
	v_lshlrev_b32_e32 v70, 16, v66
	v_and_b32_e32 v71, 0xffff0000, v66
	v_lshlrev_b32_e32 v66, 16, v67
	v_and_b32_e32 v67, 0xffff0000, v67
	v_pk_add_f32 v[58:59], v[58:59], v[64:65]
	v_pk_add_f32 v[56:57], v[56:57], v[68:69]
	v_pk_add_f32 v[62:63], v[62:63], v[66:67]
	v_pk_add_f32 v[60:61], v[60:61], v[70:71]
	v_cvt_pk_bf16_f32 v56, v56, v57
	v_cvt_pk_bf16_f32 v57, v58, v59
	v_add_u32_e32 v64, 0x28000, v133
	v_cvt_pk_bf16_f32 v58, v60, v61
	v_cvt_pk_bf16_f32 v59, v62, v63
	global_store_dwordx4 v81, v[56:59], s[74:75] sc1
	global_load_dwordx4 v[56:59], v73, s[74:75]
	v_or_b32_e32 v60, v64, v132
	v_lshlrev_b32_e32 v65, 1, v60
	s_waitcnt vmcnt(0)
	v_lshlrev_b32_e32 v60, 16, v56
	v_and_b32_e32 v61, 0xffff0000, v56
	v_lshlrev_b32_e32 v56, 16, v57
	v_and_b32_e32 v57, 0xffff0000, v57
	v_lshlrev_b32_e32 v62, 16, v58
	v_and_b32_e32 v63, 0xffff0000, v58
	v_lshlrev_b32_e32 v58, 16, v59
	v_and_b32_e32 v59, 0xffff0000, v59
	v_pk_add_f32 v[50:51], v[50:51], v[56:57]
	v_pk_add_f32 v[48:49], v[48:49], v[60:61]
	v_pk_add_f32 v[54:55], v[54:55], v[58:59]
	v_pk_add_f32 v[52:53], v[52:53], v[62:63]
	v_cvt_pk_bf16_f32 v48, v48, v49
	v_cvt_pk_bf16_f32 v49, v50, v51
	v_add_u32_e32 v56, 0x2c000, v133
	v_cvt_pk_bf16_f32 v50, v52, v53
	v_cvt_pk_bf16_f32 v51, v54, v55
	global_store_dwordx4 v73, v[48:51], s[74:75] sc1
	global_load_dwordx4 v[48:51], v65, s[74:75]
	v_or_b32_e32 v52, v56, v132
	v_lshlrev_b32_e32 v57, 1, v52
	s_waitcnt vmcnt(0)
	v_lshlrev_b32_e32 v52, 16, v48
	v_and_b32_e32 v53, 0xffff0000, v48
	v_lshlrev_b32_e32 v48, 16, v49
	v_and_b32_e32 v49, 0xffff0000, v49
	v_lshlrev_b32_e32 v54, 16, v50
	v_and_b32_e32 v55, 0xffff0000, v50
	v_lshlrev_b32_e32 v50, 16, v51
	v_and_b32_e32 v51, 0xffff0000, v51
	v_pk_add_f32 v[42:43], v[42:43], v[48:49]
	v_pk_add_f32 v[40:41], v[40:41], v[52:53]
	v_pk_add_f32 v[46:47], v[46:47], v[50:51]
	v_pk_add_f32 v[44:45], v[44:45], v[54:55]
	v_cvt_pk_bf16_f32 v40, v40, v41
	v_cvt_pk_bf16_f32 v41, v42, v43
	s_nop 0
	v_cvt_pk_bf16_f32 v42, v44, v45
	v_cvt_pk_bf16_f32 v43, v46, v47
	global_store_dwordx4 v65, v[40:43], s[74:75] sc1
	global_load_dwordx4 v[40:43], v57, s[74:75]
	v_or_b32_e32 v44, v80, v104
	v_lshlrev_b32_e32 v48, 1, v44
	s_waitcnt vmcnt(0)
; template <int N, int K, int EPI>
; __device__ __forceinline__ void gemm_phase(const bf16* __restrict__ A, const bf16* __restrict__ Bt, float* __restrict__ outf, bf16* __restrict__ outb,
;                            const float* __restrict__ ropec, const int W) {
;     ...
;             const f32x4 v0 = acc[ai][bj][m][0], v1 = acc[ai][bj][m][1];
;             if (EPI == EPI_RES) {
;               u32x4* d = (u32x4*)(obase + (size_t)((lrow * N + lcol) * 2u));
;               const u32x4 t = *d;
;               const f32x4 r0 = bf4_to_f32(u32x2{t[0], t[1]}) + v0, r1 = bf4_to_f32(u32x2{t[2], t[3]}) + v1;
;               u32x4 w = {cvtpk(r0[0], r0[1]), cvtpk(r0[2], r0[3]), cvtpk(r1[0], r1[1]), cvtpk(r1[2], r1[3])};
;               *d = w;
;             } else {
;               const float a0 = fmaxf(v0[0], 0.f), a1 = fmaxf(v0[1], 0.f), a2 = fmaxf(v0[2], 0.f), a3 = fmaxf(v0[3], 0.f);
;               const float b0 = fmaxf(v1[0], 0.f), b1 = fmaxf(v1[1], 0.f), b2 = fmaxf(v1[2], 0.f), b3 = fmaxf(v1[3], 0.f);
;               u32x4 w = {cvtpk(a0 * a0, a1 * a1), cvtpk(a2 * a2, a3 * a3), cvtpk(b0 * b0, b1 * b1), cvtpk(b2 * b2, b3 * b3)};
;               *(u32x4*)(obase + (size_t)((lrow * N + lcol) * 2u)) = w;
;             }
;           }
;     }
;     asm volatile("s_waitcnt vmcnt(0) lgkmcnt(0)" ::: "memory");
;     __syncthreads();
	v_lshlrev_b32_e32 v44, 16, v40
	v_and_b32_e32 v45, 0xffff0000, v40
	v_lshlrev_b32_e32 v40, 16, v41
	v_and_b32_e32 v41, 0xffff0000, v41
	v_lshlrev_b32_e32 v46, 16, v42
	v_and_b32_e32 v47, 0xffff0000, v42
	v_lshlrev_b32_e32 v42, 16, v43
	v_and_b32_e32 v43, 0xffff0000, v43
	v_pk_add_f32 v[34:35], v[34:35], v[40:41]
	v_pk_add_f32 v[32:33], v[32:33], v[44:45]
	v_pk_add_f32 v[38:39], v[38:39], v[42:43]
	v_pk_add_f32 v[36:37], v[36:37], v[46:47]
	v_cvt_pk_bf16_f32 v32, v32, v33
	v_cvt_pk_bf16_f32 v33, v34, v35
	s_nop 0
	v_cvt_pk_bf16_f32 v34, v36, v37
	v_cvt_pk_bf16_f32 v35, v38, v39
	global_store_dwordx4 v57, v[32:35], s[74:75] sc1
	global_load_dwordx4 v[32:35], v48, s[74:75]
	v_or_b32_e32 v36, v72, v104
	v_lshlrev_b32_e32 v40, 1, v36
	s_waitcnt vmcnt(0)
	v_lshlrev_b32_e32 v36, 16, v32
	v_and_b32_e32 v37, 0xffff0000, v32
	v_lshlrev_b32_e32 v32, 16, v33
	v_and_b32_e32 v33, 0xffff0000, v33
	v_lshlrev_b32_e32 v38, 16, v34
	v_and_b32_e32 v39, 0xffff0000, v34
	v_lshlrev_b32_e32 v34, 16, v35
	v_and_b32_e32 v35, 0xffff0000, v35
	v_pk_add_f32 v[26:27], v[26:27], v[32:33]
	v_pk_add_f32 v[24:25], v[24:25], v[36:37]
	v_pk_add_f32 v[30:31], v[30:31], v[34:35]
	v_pk_add_f32 v[28:29], v[28:29], v[38:39]
	v_cvt_pk_bf16_f32 v24, v24, v25
	v_cvt_pk_bf16_f32 v25, v26, v27
	s_nop 0
	v_cvt_pk_bf16_f32 v26, v28, v29
	v_cvt_pk_bf16_f32 v27, v30, v31
	global_store_dwordx4 v48, v[24:27], s[74:75] sc1
	global_load_dwordx4 v[24:27], v40, s[74:75]
	v_or_b32_e32 v28, v64, v104
	v_lshlrev_b32_e32 v32, 1, v28
	s_waitcnt vmcnt(0)
	v_lshlrev_b32_e32 v28, 16, v24
	v_and_b32_e32 v29, 0xffff0000, v24
	v_lshlrev_b32_e32 v24, 16, v25
	v_and_b32_e32 v25, 0xffff0000, v25
	v_lshlrev_b32_e32 v30, 16, v26
	v_and_b32_e32 v31, 0xffff0000, v26
	v_lshlrev_b32_e32 v26, 16, v27
	v_and_b32_e32 v27, 0xffff0000, v27
	v_pk_add_f32 v[18:19], v[18:19], v[24:25]
	v_pk_add_f32 v[16:17], v[16:17], v[28:29]
	v_pk_add_f32 v[22:23], v[22:23], v[26:27]
	v_pk_add_f32 v[20:21], v[20:21], v[30:31]
	v_cvt_pk_bf16_f32 v16, v16, v17
	v_cvt_pk_bf16_f32 v17, v18, v19
	s_nop 0
	v_cvt_pk_bf16_f32 v18, v20, v21
	v_cvt_pk_bf16_f32 v19, v22, v23
	global_store_dwordx4 v40, v[16:19], s[74:75] sc1
	global_load_dwordx4 v[16:19], v32, s[74:75]
	v_or_b32_e32 v20, v56, v104
	v_lshlrev_b32_e32 v24, 1, v20
	s_waitcnt vmcnt(0)
	v_lshlrev_b32_e32 v20, 16, v16
	v_and_b32_e32 v21, 0xffff0000, v16
	v_lshlrev_b32_e32 v16, 16, v17
	v_and_b32_e32 v17, 0xffff0000, v17
	v_lshlrev_b32_e32 v22, 16, v18
	v_and_b32_e32 v23, 0xffff0000, v18
	v_lshlrev_b32_e32 v18, 16, v19
	v_and_b32_e32 v19, 0xffff0000, v19
	v_pk_add_f32 v[10:11], v[10:11], v[16:17]
	v_pk_add_f32 v[8:9], v[8:9], v[20:21]
	v_pk_add_f32 v[14:15], v[14:15], v[18:19]
	v_pk_add_f32 v[12:13], v[12:13], v[22:23]
	v_cvt_pk_bf16_f32 v8, v8, v9
	v_cvt_pk_bf16_f32 v9, v10, v11
	s_nop 0
	v_cvt_pk_bf16_f32 v10, v12, v13
	v_cvt_pk_bf16_f32 v11, v14, v15
	global_store_dwordx4 v32, v[8:11], s[74:75] sc1
	global_load_dwordx4 v[8:11], v24, s[74:75]
	s_waitcnt vmcnt(0)
	v_lshlrev_b32_e32 v12, 16, v8
	v_and_b32_e32 v13, 0xffff0000, v8
	v_lshlrev_b32_e32 v8, 16, v9
	v_and_b32_e32 v9, 0xffff0000, v9
	v_lshlrev_b32_e32 v14, 16, v10
	v_and_b32_e32 v15, 0xffff0000, v10
	v_lshlrev_b32_e32 v10, 16, v11
	v_and_b32_e32 v11, 0xffff0000, v11
	v_pk_add_f32 v[6:7], v[6:7], v[8:9]
	v_pk_add_f32 v[8:9], v[2:3], v[10:11]
	v_pk_add_f32 v[2:3], v[0:1], v[14:15]
	v_pk_add_f32 v[4:5], v[4:5], v[12:13]
	s_nop 0
	v_cvt_pk_bf16_f32 v0, v4, v5
	v_cvt_pk_bf16_f32 v1, v6, v7
	v_cvt_pk_bf16_f32 v2, v2, v3
	v_cvt_pk_bf16_f32 v3, v8, v9
	global_store_dwordx4 v24, v[0:3], s[74:75] sc1
	s_waitcnt vmcnt(0) lgkmcnt(0)
	s_barrier
	s_cbranch_scc0 .LBB0_372

; template <int N, int K, int EPI>
; __device__ __forceinline__ void gemm_phase(const bf16* __restrict__ A, const bf16* __restrict__ Bt, float* __restrict__ outf, bf16* __restrict__ outb,
;                            const float* __restrict__ ropec, const int W) {
;     ...
;       char* obase = (char*)(outb + (size_t)brow * N + bcol);
; #pragma unroll
;       for (int ai = 0; ai < 2; ++ai)
; #pragma unroll
;         for (int bj = 0; bj < 2; ++bj)
; #pragma unroll
;           for (int m = 0; m < 4; ++m) {
;             const unsigned lrow = ai * HALF + wr * 64 + m * 16 + efr;
;             const unsigned lcol = bj * HALF + wcb + efq * 8;
;             const f32x4 v0 = acc[ai][bj][m][0], v1 = acc[ai][bj][m][1];
;             if (EPI == EPI_RES) {
;               u32x4* d = (u32x4*)(obase + (size_t)((lrow * N + lcol) * 2u));
;               const u32x4 t = *d;
;               const f32x4 r0 = bf4_to_f32(u32x2{t[0], t[1]}) + v0, r1 = bf4_to_f32(u32x2{t[2], t[3]}) + v1;
;               u32x4 w = {cvtpk(r0[0], r0[1]), cvtpk(r0[2], r0[3]), cvtpk(r1[0], r1[1]), cvtpk(r1[2], r1[3])};
;               *d = w;
.LBB0_418:
	v_mbcnt_lo_u32_b32 v133, -1, 0
	v_mbcnt_hi_u32_b32 v133, -1, v133
	s_lshl_b64 s[70:71], s[70:71], 11
	v_lshrrev_b32_e32 v132, 1, v133
	v_lshlrev_b32_e32 v133, 10, v133
	s_add_u32 s55, s66, s70
	v_and_b32_e32 v133, 0x3c00, v133
	s_addc_u32 s70, s67, s71
	s_lshl_b64 s[68:69], s[68:69], 1
	v_and_or_b32 v132, v132, 24, s4
	v_or_b32_e32 v133, s3, v133
	s_add_u32 s68, s55, s68
	v_or_b32_e32 v158, v133, v132
	s_addc_u32 s69, s70, s69
	v_lshlrev_b32_e32 v166, 1, v158
	global_load_dwordx4 v[158:161], v166, s[68:69]
	v_or_b32_e32 v167, 0x4000, v133
	v_or_b32_e32 v162, v167, v132
	v_lshlrev_b32_e32 v168, 1, v162
	s_add_i32 s2, s2, s33
	s_cmpk_lt_i32 s2, 0x200
	s_waitcnt vmcnt(0)
	v_lshlrev_b32_e32 v162, 16, v158
	v_and_b32_e32 v163, 0xffff0000, v158
	v_lshlrev_b32_e32 v158, 16, v159
	v_and_b32_e32 v159, 0xffff0000, v159
	v_lshlrev_b32_e32 v164, 16, v160
	v_and_b32_e32 v165, 0xffff0000, v160
	v_lshlrev_b32_e32 v160, 16, v161
	v_and_b32_e32 v161, 0xffff0000, v161
	v_pk_add_f32 v[122:123], v[122:123], v[158:159]
	v_pk_add_f32 v[120:121], v[120:121], v[162:163]
	v_pk_add_f32 v[126:127], v[126:127], v[160:161]
	v_pk_add_f32 v[124:125], v[124:125], v[164:165]
	v_cvt_pk_bf16_f32 v120, v120, v121
	v_cvt_pk_bf16_f32 v121, v122, v123
	v_or_b32_e32 v158, 0x8000, v133
	v_cvt_pk_bf16_f32 v122, v124, v125
	v_cvt_pk_bf16_f32 v123, v126, v127
	global_store_dwordx4 v166, v[120:123], s[68:69] sc1
	global_load_dwordx4 v[120:123], v168, s[68:69]
	v_or_b32_e32 v124, v158, v132
	v_lshlrev_b32_e32 v159, 1, v124
	s_waitcnt vmcnt(0)
	v_lshlrev_b32_e32 v124, 16, v120
	v_and_b32_e32 v125, 0xffff0000, v120
	v_lshlrev_b32_e32 v120, 16, v121
	v_and_b32_e32 v121, 0xffff0000, v121
	v_lshlrev_b32_e32 v126, 16, v122
	v_and_b32_e32 v127, 0xffff0000, v122
	v_lshlrev_b32_e32 v122, 16, v123
	v_and_b32_e32 v123, 0xffff0000, v123
	v_pk_add_f32 v[114:115], v[114:115], v[120:121]
	v_pk_add_f32 v[112:113], v[112:113], v[124:125]
	v_pk_add_f32 v[118:119], v[118:119], v[122:123]
	v_pk_add_f32 v[116:117], v[116:117], v[126:127]
	v_cvt_pk_bf16_f32 v112, v112, v113
	v_cvt_pk_bf16_f32 v113, v114, v115
	v_or_b32_e32 v120, 0xc000, v133
	v_cvt_pk_bf16_f32 v114, v116, v117
	v_cvt_pk_bf16_f32 v115, v118, v119
	global_store_dwordx4 v168, v[112:115], s[68:69] sc1
	global_load_dwordx4 v[112:115], v159, s[68:69]
	v_or_b32_e32 v116, v120, v132
	v_lshlrev_b32_e32 v121, 1, v116
	s_waitcnt vmcnt(0)
	v_lshlrev_b32_e32 v116, 16, v112
	v_and_b32_e32 v117, 0xffff0000, v112
	v_lshlrev_b32_e32 v112, 16, v113
	v_and_b32_e32 v113, 0xffff0000, v113
	v_lshlrev_b32_e32 v118, 16, v114
	v_and_b32_e32 v119, 0xffff0000, v114
	v_lshlrev_b32_e32 v114, 16, v115
	v_and_b32_e32 v115, 0xffff0000, v115
	v_pk_add_f32 v[106:107], v[106:107], v[112:113]
	v_pk_add_f32 v[104:105], v[104:105], v[116:117]
	v_pk_add_f32 v[110:111], v[110:111], v[114:115]
	v_pk_add_f32 v[108:109], v[108:109], v[118:119]
	v_cvt_pk_bf16_f32 v104, v104, v105
	v_cvt_pk_bf16_f32 v105, v106, v107
	s_nop 0
	v_cvt_pk_bf16_f32 v106, v108, v109
	v_cvt_pk_bf16_f32 v107, v110, v111
	global_store_dwordx4 v159, v[104:107], s[68:69] sc1
	global_load_dwordx4 v[106:109], v121, s[68:69]
	s_waitcnt vmcnt(0)
	v_lshlrev_b32_e32 v110, 16, v106
	v_or_b32_e32 v104, 0x80, v132
	v_and_b32_e32 v111, 0xffff0000, v106
	v_lshlrev_b32_e32 v106, 16, v107
	v_and_b32_e32 v107, 0xffff0000, v107
	v_or_b32_e32 v105, v104, v133
	v_lshlrev_b32_e32 v112, 16, v108
	v_and_b32_e32 v113, 0xffff0000, v108
	v_lshlrev_b32_e32 v108, 16, v109
	v_and_b32_e32 v109, 0xffff0000, v109
	v_pk_add_f32 v[98:99], v[98:99], v[106:107]
	v_pk_add_f32 v[96:97], v[96:97], v[110:111]
	v_lshlrev_b32_e32 v105, 1, v105
	v_pk_add_f32 v[102:103], v[102:103], v[108:109]
	v_pk_add_f32 v[100:101], v[100:101], v[112:113]
	v_cvt_pk_bf16_f32 v96, v96, v97
	v_cvt_pk_bf16_f32 v97, v98, v99
	s_nop 0
	v_cvt_pk_bf16_f32 v98, v100, v101
	v_cvt_pk_bf16_f32 v99, v102, v103
	global_store_dwordx4 v121, v[96:99], s[68:69] sc1
	global_load_dwordx4 v[96:99], v105, s[68:69]
	v_or_b32_e32 v100, v167, v104
	v_lshlrev_b32_e32 v106, 1, v100
	s_waitcnt vmcnt(0)
	v_lshlrev_b32_e32 v100, 16, v96
	v_and_b32_e32 v101, 0xffff0000, v96
	v_lshlrev_b32_e32 v96, 16, v97
	v_and_b32_e32 v97, 0xffff0000, v97
	v_lshlrev_b32_e32 v102, 16, v98
	v_and_b32_e32 v103, 0xffff0000, v98
	v_lshlrev_b32_e32 v98, 16, v99
	v_and_b32_e32 v99, 0xffff0000, v99
	v_pk_add_f32 v[90:91], v[90:91], v[96:97]
	v_pk_add_f32 v[88:89], v[88:89], v[100:101]
	v_pk_add_f32 v[94:95], v[94:95], v[98:99]
	v_pk_add_f32 v[92:93], v[92:93], v[102:103]
	v_cvt_pk_bf16_f32 v88, v88, v89
	v_cvt_pk_bf16_f32 v89, v90, v91
	s_nop 0
	v_cvt_pk_bf16_f32 v90, v92, v93
	v_cvt_pk_bf16_f32 v91, v94, v95
	global_store_dwordx4 v105, v[88:91], s[68:69] sc1
	global_load_dwordx4 v[88:91], v106, s[68:69]
	v_or_b32_e32 v92, v158, v104
	v_lshlrev_b32_e32 v96, 1, v92
	s_waitcnt vmcnt(0)
	v_lshlrev_b32_e32 v92, 16, v88
	v_and_b32_e32 v93, 0xffff0000, v88
	v_lshlrev_b32_e32 v88, 16, v89
	v_and_b32_e32 v89, 0xffff0000, v89
	v_lshlrev_b32_e32 v94, 16, v90
	v_and_b32_e32 v95, 0xffff0000, v90
	v_lshlrev_b32_e32 v90, 16, v91
	v_and_b32_e32 v91, 0xffff0000, v91
	v_pk_add_f32 v[82:83], v[82:83], v[88:89]
	v_pk_add_f32 v[80:81], v[80:81], v[92:93]
	v_pk_add_f32 v[86:87], v[86:87], v[90:91]
	v_pk_add_f32 v[84:85], v[84:85], v[94:95]
	v_cvt_pk_bf16_f32 v80, v80, v81
	v_cvt_pk_bf16_f32 v81, v82, v83
	s_nop 0
	v_cvt_pk_bf16_f32 v82, v84, v85
	v_cvt_pk_bf16_f32 v83, v86, v87
	global_store_dwordx4 v106, v[80:83], s[68:69] sc1
	global_load_dwordx4 v[80:83], v96, s[68:69]
	v_or_b32_e32 v84, v120, v104
	v_lshlrev_b32_e32 v88, 1, v84
	s_waitcnt vmcnt(0)
; template <int N, int K, int EPI>
; __device__ __forceinline__ void gemm_phase(const bf16* __restrict__ A, const bf16* __restrict__ Bt, float* __restrict__ outf, bf16* __restrict__ outb,
;                            const float* __restrict__ ropec, const int W) {
;     ...
;             const f32x4 v0 = acc[ai][bj][m][0], v1 = acc[ai][bj][m][1];
;             if (EPI == EPI_RES) {
;               u32x4* d = (u32x4*)(obase + (size_t)((lrow * N + lcol) * 2u));
;               const u32x4 t = *d;
;               const f32x4 r0 = bf4_to_f32(u32x2{t[0], t[1]}) + v0, r1 = bf4_to_f32(u32x2{t[2], t[3]}) + v1;
;               u32x4 w = {cvtpk(r0[0], r0[1]), cvtpk(r0[2], r0[3]), cvtpk(r1[0], r1[1]), cvtpk(r1[2], r1[3])};
;               *d = w;
	v_lshlrev_b32_e32 v84, 16, v80
	v_and_b32_e32 v85, 0xffff0000, v80
	v_lshlrev_b32_e32 v80, 16, v81
	v_and_b32_e32 v81, 0xffff0000, v81
	v_lshlrev_b32_e32 v86, 16, v82
	v_and_b32_e32 v87, 0xffff0000, v82
	v_lshlrev_b32_e32 v82, 16, v83
	v_and_b32_e32 v83, 0xffff0000, v83
	v_pk_add_f32 v[74:75], v[74:75], v[80:81]
	v_pk_add_f32 v[72:73], v[72:73], v[84:85]
	v_pk_add_f32 v[78:79], v[78:79], v[82:83]
	v_pk_add_f32 v[76:77], v[76:77], v[86:87]
	v_cvt_pk_bf16_f32 v72, v72, v73
	v_cvt_pk_bf16_f32 v73, v74, v75
	v_add_u32_e32 v80, 0x20000, v133
	v_cvt_pk_bf16_f32 v74, v76, v77
	v_cvt_pk_bf16_f32 v75, v78, v79
	global_store_dwordx4 v96, v[72:75], s[68:69] sc1
	global_load_dwordx4 v[72:75], v88, s[68:69]
	v_or_b32_e32 v76, v80, v132
	v_lshlrev_b32_e32 v81, 1, v76
	s_waitcnt vmcnt(0)
	v_lshlrev_b32_e32 v76, 16, v72
	v_and_b32_e32 v77, 0xffff0000, v72
	v_lshlrev_b32_e32 v72, 16, v73
	v_and_b32_e32 v73, 0xffff0000, v73
	v_lshlrev_b32_e32 v78, 16, v74
	v_and_b32_e32 v79, 0xffff0000, v74
	v_lshlrev_b32_e32 v74, 16, v75
	v_and_b32_e32 v75, 0xffff0000, v75
	v_pk_add_f32 v[66:67], v[66:67], v[72:73]
	v_pk_add_f32 v[64:65], v[64:65], v[76:77]
	v_pk_add_f32 v[70:71], v[70:71], v[74:75]
	v_pk_add_f32 v[68:69], v[68:69], v[78:79]
	v_cvt_pk_bf16_f32 v64, v64, v65
	v_cvt_pk_bf16_f32 v65, v66, v67
	v_add_u32_e32 v72, 0x24000, v133
	v_cvt_pk_bf16_f32 v66, v68, v69
	v_cvt_pk_bf16_f32 v67, v70, v71
	global_store_dwordx4 v88, v[64:67], s[68:69] sc1
	global_load_dwordx4 v[64:67], v81, s[68:69]
	v_or_b32_e32 v68, v72, v132
	v_lshlrev_b32_e32 v73, 1, v68
	s_waitcnt vmcnt(0)
	v_lshlrev_b32_e32 v68, 16, v64
	v_and_b32_e32 v69, 0xffff0000, v64
	v_lshlrev_b32_e32 v64, 16, v65
	v_and_b32_e32 v65, 0xffff0000, v65
	v_lshlrev_b32_e32 v70, 16, v66
	v_and_b32_e32 v71, 0xffff0000, v66
	v_lshlrev_b32_e32 v66, 16, v67
	v_and_b32_e32 v67, 0xffff0000, v67
	v_pk_add_f32 v[58:59], v[58:59], v[64:65]
	v_pk_add_f32 v[56:57], v[56:57], v[68:69]
	v_pk_add_f32 v[62:63], v[62:63], v[66:67]
	v_pk_add_f32 v[60:61], v[60:61], v[70:71]
	v_cvt_pk_bf16_f32 v56, v56, v57
	v_cvt_pk_bf16_f32 v57, v58, v59
	v_add_u32_e32 v64, 0x28000, v133
	v_cvt_pk_bf16_f32 v58, v60, v61
	v_cvt_pk_bf16_f32 v59, v62, v63
	global_store_dwordx4 v81, v[56:59], s[68:69] sc1
	global_load_dwordx4 v[56:59], v73, s[68:69]
	v_or_b32_e32 v60, v64, v132
	v_lshlrev_b32_e32 v65, 1, v60
	s_waitcnt vmcnt(0)
	v_lshlrev_b32_e32 v60, 16, v56
	v_and_b32_e32 v61, 0xffff0000, v56
	v_lshlrev_b32_e32 v56, 16, v57
	v_and_b32_e32 v57, 0xffff0000, v57
	v_lshlrev_b32_e32 v62, 16, v58
	v_and_b32_e32 v63, 0xffff0000, v58
	v_lshlrev_b32_e32 v58, 16, v59
	v_and_b32_e32 v59, 0xffff0000, v59
	v_pk_add_f32 v[50:51], v[50:51], v[56:57]
	v_pk_add_f32 v[48:49], v[48:49], v[60:61]
	v_pk_add_f32 v[54:55], v[54:55], v[58:59]
	v_pk_add_f32 v[52:53], v[52:53], v[62:63]
	v_cvt_pk_bf16_f32 v48, v48, v49
	v_cvt_pk_bf16_f32 v49, v50, v51
	v_add_u32_e32 v56, 0x2c000, v133
	v_cvt_pk_bf16_f32 v50, v52, v53
	v_cvt_pk_bf16_f32 v51, v54, v55
	global_store_dwordx4 v73, v[48:51], s[68:69] sc1
	global_load_dwordx4 v[48:51], v65, s[68:69]
	v_or_b32_e32 v52, v56, v132
	v_lshlrev_b32_e32 v57, 1, v52
	s_waitcnt vmcnt(0)
	v_lshlrev_b32_e32 v52, 16, v48
	v_and_b32_e32 v53, 0xffff0000, v48
	v_lshlrev_b32_e32 v48, 16, v49
	v_and_b32_e32 v49, 0xffff0000, v49
	v_lshlrev_b32_e32 v54, 16, v50
	v_and_b32_e32 v55, 0xffff0000, v50
	v_lshlrev_b32_e32 v50, 16, v51
	v_and_b32_e32 v51, 0xffff0000, v51
	v_pk_add_f32 v[42:43], v[42:43], v[48:49]
	v_pk_add_f32 v[40:41], v[40:41], v[52:53]
	v_pk_add_f32 v[46:47], v[46:47], v[50:51]
	v_pk_add_f32 v[44:45], v[44:45], v[54:55]
	v_cvt_pk_bf16_f32 v40, v40, v41
	v_cvt_pk_bf16_f32 v41, v42, v43
	s_nop 0
	v_cvt_pk_bf16_f32 v42, v44, v45
	v_cvt_pk_bf16_f32 v43, v46, v47
	global_store_dwordx4 v65, v[40:43], s[68:69] sc1
	global_load_dwordx4 v[40:43], v57, s[68:69]
	v_or_b32_e32 v44, v80, v104
	v_lshlrev_b32_e32 v48, 1, v44
	s_waitcnt vmcnt(0)
; template <int N, int K, int EPI>
; __device__ __forceinline__ void gemm_phase(const bf16* __restrict__ A, const bf16* __restrict__ Bt, float* __restrict__ outf, bf16* __restrict__ outb,
;                            const float* __restrict__ ropec, const int W) {
;     ...
;             const f32x4 v0 = acc[ai][bj][m][0], v1 = acc[ai][bj][m][1];
;             if (EPI == EPI_RES) {
;               u32x4* d = (u32x4*)(obase + (size_t)((lrow * N + lcol) * 2u));
;               const u32x4 t = *d;
;               const f32x4 r0 = bf4_to_f32(u32x2{t[0], t[1]}) + v0, r1 = bf4_to_f32(u32x2{t[2], t[3]}) + v1;
;               u32x4 w = {cvtpk(r0[0], r0[1]), cvtpk(r0[2], r0[3]), cvtpk(r1[0], r1[1]), cvtpk(r1[2], r1[3])};
;               *d = w;
;             } else {
;               const float a0 = fmaxf(v0[0], 0.f), a1 = fmaxf(v0[1], 0.f), a2 = fmaxf(v0[2], 0.f), a3 = fmaxf(v0[3], 0.f);
;               const float b0 = fmaxf(v1[0], 0.f), b1 = fmaxf(v1[1], 0.f), b2 = fmaxf(v1[2], 0.f), b3 = fmaxf(v1[3], 0.f);
;               u32x4 w = {cvtpk(a0 * a0, a1 * a1), cvtpk(a2 * a2, a3 * a3), cvtpk(b0 * b0, b1 * b1), cvtpk(b2 * b2, b3 * b3)};
;               *(u32x4*)(obase + (size_t)((lrow * N + lcol) * 2u)) = w;
;             }
;           }
;     }
;     asm volatile("s_waitcnt vmcnt(0) lgkmcnt(0)" ::: "memory");
;     __syncthreads();
	v_lshlrev_b32_e32 v44, 16, v40
	v_and_b32_e32 v45, 0xffff0000, v40
	v_lshlrev_b32_e32 v40, 16, v41
	v_and_b32_e32 v41, 0xffff0000, v41
	v_lshlrev_b32_e32 v46, 16, v42
	v_and_b32_e32 v47, 0xffff0000, v42
	v_lshlrev_b32_e32 v42, 16, v43
	v_and_b32_e32 v43, 0xffff0000, v43
	v_pk_add_f32 v[34:35], v[34:35], v[40:41]
	v_pk_add_f32 v[32:33], v[32:33], v[44:45]
	v_pk_add_f32 v[38:39], v[38:39], v[42:43]
	v_pk_add_f32 v[36:37], v[36:37], v[46:47]
	v_cvt_pk_bf16_f32 v32, v32, v33
	v_cvt_pk_bf16_f32 v33, v34, v35
	s_nop 0
	v_cvt_pk_bf16_f32 v34, v36, v37
	v_cvt_pk_bf16_f32 v35, v38, v39
	global_store_dwordx4 v57, v[32:35], s[68:69] sc1
	global_load_dwordx4 v[32:35], v48, s[68:69]
	v_or_b32_e32 v36, v72, v104
	v_lshlrev_b32_e32 v40, 1, v36
	s_waitcnt vmcnt(0)
	v_lshlrev_b32_e32 v36, 16, v32
	v_and_b32_e32 v37, 0xffff0000, v32
	v_lshlrev_b32_e32 v32, 16, v33
	v_and_b32_e32 v33, 0xffff0000, v33
	v_lshlrev_b32_e32 v38, 16, v34
	v_and_b32_e32 v39, 0xffff0000, v34
	v_lshlrev_b32_e32 v34, 16, v35
	v_and_b32_e32 v35, 0xffff0000, v35
	v_pk_add_f32 v[26:27], v[26:27], v[32:33]
	v_pk_add_f32 v[24:25], v[24:25], v[36:37]
	v_pk_add_f32 v[30:31], v[30:31], v[34:35]
	v_pk_add_f32 v[28:29], v[28:29], v[38:39]
	v_cvt_pk_bf16_f32 v24, v24, v25
	v_cvt_pk_bf16_f32 v25, v26, v27
	s_nop 0
	v_cvt_pk_bf16_f32 v26, v28, v29
	v_cvt_pk_bf16_f32 v27, v30, v31
	global_store_dwordx4 v48, v[24:27], s[68:69] sc1
	global_load_dwordx4 v[24:27], v40, s[68:69]
	v_or_b32_e32 v28, v64, v104
	v_lshlrev_b32_e32 v32, 1, v28
	s_waitcnt vmcnt(0)
	v_lshlrev_b32_e32 v28, 16, v24
	v_and_b32_e32 v29, 0xffff0000, v24
	v_lshlrev_b32_e32 v24, 16, v25
	v_and_b32_e32 v25, 0xffff0000, v25
	v_lshlrev_b32_e32 v30, 16, v26
	v_and_b32_e32 v31, 0xffff0000, v26
	v_lshlrev_b32_e32 v26, 16, v27
	v_and_b32_e32 v27, 0xffff0000, v27
	v_pk_add_f32 v[18:19], v[18:19], v[24:25]
	v_pk_add_f32 v[16:17], v[16:17], v[28:29]
	v_pk_add_f32 v[22:23], v[22:23], v[26:27]
	v_pk_add_f32 v[20:21], v[20:21], v[30:31]
	v_cvt_pk_bf16_f32 v16, v16, v17
	v_cvt_pk_bf16_f32 v17, v18, v19
	s_nop 0
	v_cvt_pk_bf16_f32 v18, v20, v21
	v_cvt_pk_bf16_f32 v19, v22, v23
	global_store_dwordx4 v40, v[16:19], s[68:69] sc1
	global_load_dwordx4 v[16:19], v32, s[68:69]
	v_or_b32_e32 v20, v56, v104
	v_lshlrev_b32_e32 v24, 1, v20
	s_waitcnt vmcnt(0)
	v_lshlrev_b32_e32 v20, 16, v16
	v_and_b32_e32 v21, 0xffff0000, v16
	v_lshlrev_b32_e32 v16, 16, v17
	v_and_b32_e32 v17, 0xffff0000, v17
	v_lshlrev_b32_e32 v22, 16, v18
	v_and_b32_e32 v23, 0xffff0000, v18
	v_lshlrev_b32_e32 v18, 16, v19
	v_and_b32_e32 v19, 0xffff0000, v19
	v_pk_add_f32 v[10:11], v[10:11], v[16:17]
	v_pk_add_f32 v[8:9], v[8:9], v[20:21]
	v_pk_add_f32 v[14:15], v[14:15], v[18:19]
	v_pk_add_f32 v[12:13], v[12:13], v[22:23]
	v_cvt_pk_bf16_f32 v8, v8, v9
	v_cvt_pk_bf16_f32 v9, v10, v11
	s_nop 0
	v_cvt_pk_bf16_f32 v10, v12, v13
	v_cvt_pk_bf16_f32 v11, v14, v15
	global_store_dwordx4 v32, v[8:11], s[68:69] sc1
	global_load_dwordx4 v[8:11], v24, s[68:69]
	s_waitcnt vmcnt(0)
	v_lshlrev_b32_e32 v12, 16, v8
	v_and_b32_e32 v13, 0xffff0000, v8
	v_lshlrev_b32_e32 v8, 16, v9
	v_and_b32_e32 v9, 0xffff0000, v9
	v_lshlrev_b32_e32 v14, 16, v10
	v_and_b32_e32 v15, 0xffff0000, v10
	v_lshlrev_b32_e32 v10, 16, v11
	v_and_b32_e32 v11, 0xffff0000, v11
	v_pk_add_f32 v[6:7], v[6:7], v[8:9]
	v_pk_add_f32 v[8:9], v[2:3], v[10:11]
	v_pk_add_f32 v[2:3], v[0:1], v[14:15]
	v_pk_add_f32 v[4:5], v[4:5], v[12:13]
	s_nop 0
	v_cvt_pk_bf16_f32 v0, v4, v5
	v_cvt_pk_bf16_f32 v1, v6, v7
	v_cvt_pk_bf16_f32 v2, v2, v3
	v_cvt_pk_bf16_f32 v3, v8, v9
	global_store_dwordx4 v24, v[0:3], s[68:69] sc1
	s_waitcnt vmcnt(0) lgkmcnt(0)
	s_barrier
	s_cbranch_scc0 .LBB0_429

; template <int MODE>
; __device__ __forceinline__ void rmsnorm_phase(const Params& p, const float* __restrict__ g, bf16* __restrict__ dstb, const int W) {
;     ...
;       for (int q = 0; q < NR; ++q) { const int row = (row0 + q * stride < T) ? row0 + q * stride : row0;
;         const bf16* src = resb + (size_t)row * DM;
; #pragma unroll
;         for (int i = 0; i < 4; ++i) t[q][i] = *reinterpret_cast<const u32x2*>(src + i * 256 + lane * 4); }
; #pragma unroll
;       for (int q = 0; q < NR; ++q)
; #pragma unroll
;         for (int i = 0; i < 4; ++i) v[q][i] = bf4_to_f32(t[q][i]);
;     }
; #pragma unroll
;     for (int q = 0; q < NR; ++q) {
;       const int row = row0 + q * stride;
;       if (row >= T) break;
;       float ss = 0.f;
; #pragma unroll
;       for (int i = 0; i < 4; ++i) ss += v[q][i][0] * v[q][i][0] + v[q][i][1] * v[q][i][1] + v[q][i][2] * v[q][i][2] + v[q][i][3] * v[q][i][3];
;       ss = wave_sum(ss, lane);
;       const float rstd = rsqrtf(ss * (1.f / DM) + EPS);
; #pragma unroll
;       for (int i = 0; i < 4; ++i) {
;         if (MODE == 0) { u32x2 wr_ = {cvtpk(v[q][i][0], v[q][i][1]), cvtpk(v[q][i][2], v[q][i][3])};
;                          *reinterpret_cast<u32x2*>(resb + (size_t)row * DM + i * 256 + lane * 4) = wr_; }
;         f32x4 y = {v[q][i][0] * rstd * gv[i][0], v[q][i][1] * rstd * gv[i][1], v[q][i][2] * rstd * gv[i][2], v[q][i][3] * rstd * gv[i][3]};
;         if (MODE == 2) *reinterpret_cast<f32x4*>(p.out + (size_t)row * DM + i * 256 + lane * 4) = y;
.LBB0_440:
	s_add_i32 s0, s54, s10
	s_cmp_lt_i32 s0, 0x8000
	s_cselect_b32 s2, s0, s54
	s_ashr_i32 s3, s2, 31
	s_lshl_b64 s[14:15], s[2:3], 11
	s_add_i32 s6, s11, s54
	s_cmp_lt_i32 s6, 0x8000
	s_cselect_b64 s[8:9], -1, 0
	s_and_b64 s[2:3], s[8:9], exec
	s_cselect_b32 s2, s6, s54
	s_ashr_i32 s3, s2, 31
	s_lshl_b64 s[16:17], s[2:3], 11
	s_add_i32 s2, s12, s54
	s_cmp_lt_i32 s2, 0x8000
	s_cselect_b64 s[4:5], -1, 0
	s_and_b64 s[18:19], s[4:5], exec
	s_cselect_b32 s18, s2, s54
	s_ashr_i32 s55, s54, 31
	s_lshl_b64 s[20:21], s[54:55], 11
	s_waitcnt vmcnt(4)
	v_lshl_add_u64 v[20:21], v[16:17], 0, s[20:21]
	global_load_dwordx2 v[52:53], v[20:21], off
	global_load_dwordx2 v[54:55], v[20:21], off offset:512
	global_load_dwordx2 v[56:57], v[20:21], off offset:1024
	global_load_dwordx2 v[58:59], v[20:21], off offset:1536
	s_ashr_i32 s19, s18, 31
	v_lshl_add_u64 v[20:21], v[16:17], 0, s[14:15]
	s_lshl_b64 s[14:15], s[18:19], 11
	global_load_dwordx2 v[42:43], v[20:21], off
	global_load_dwordx2 v[40:41], v[20:21], off offset:512
	global_load_dwordx2 v[38:39], v[20:21], off offset:1024
	global_load_dwordx2 v[36:37], v[20:21], off offset:1536
	v_lshl_add_u64 v[20:21], v[16:17], 0, s[16:17]
	v_lshl_add_u64 v[60:61], v[16:17], 0, s[14:15]
	global_load_dwordx2 v[34:35], v[20:21], off
	global_load_dwordx2 v[32:33], v[20:21], off offset:512
	global_load_dwordx2 v[30:31], v[20:21], off offset:1024
	global_load_dwordx2 v[28:29], v[20:21], off offset:1536
	global_load_dwordx2 v[26:27], v[60:61], off
	global_load_dwordx2 v[24:25], v[60:61], off offset:512
	global_load_dwordx2 v[22:23], v[60:61], off offset:1024
	s_nop 0
	global_load_dwordx2 v[20:21], v[60:61], off offset:1536
	s_lshl_b64 s[14:15], s[54:55], 12
	s_cmpk_gt_i32 s0, 0x7fff
	s_waitcnt vmcnt(15)
	v_and_b32_e32 v61, 0xffff0000, v52
	s_waitcnt vmcnt(14)
	v_and_b32_e32 v63, 0xffff0000, v54
	v_lshlrev_b32_e32 v60, 16, v52
	v_lshlrev_b32_e32 v62, 16, v54
	s_waitcnt vmcnt(13)
	v_and_b32_e32 v65, 0xffff0000, v56
	s_waitcnt vmcnt(12)
	v_and_b32_e32 v67, 0xffff0000, v58
	v_mov_b32_e32 v70, v63
	v_mov_b32_e32 v71, v61
	v_lshlrev_b32_e32 v52, 16, v53
	v_lshlrev_b32_e32 v54, 16, v55
	v_lshlrev_b32_e32 v64, 16, v56
	v_lshlrev_b32_e32 v66, 16, v58
	v_mov_b32_e32 v68, v62
	v_mov_b32_e32 v69, v60
	v_mov_b32_e32 v78, v67
	v_mov_b32_e32 v79, v65
	v_pk_mul_f32 v[70:71], v[70:71], v[70:71]
	v_and_b32_e32 v53, 0xffff0000, v53
	v_and_b32_e32 v55, 0xffff0000, v55
	v_lshlrev_b32_e32 v56, 16, v57
	v_lshlrev_b32_e32 v58, 16, v59
	v_mov_b32_e32 v72, v54
	v_mov_b32_e32 v73, v52
	v_mov_b32_e32 v76, v66
	v_mov_b32_e32 v77, v64
	v_pk_mul_f32 v[78:79], v[78:79], v[78:79]
	v_pk_fma_f32 v[68:69], v[68:69], v[68:69], v[70:71]
	v_and_b32_e32 v57, 0xffff0000, v57
	v_and_b32_e32 v59, 0xffff0000, v59
	v_mov_b32_e32 v74, v55
	v_mov_b32_e32 v75, v53
	v_mov_b32_e32 v80, v58
	v_mov_b32_e32 v81, v56
	v_pk_fma_f32 v[70:71], v[76:77], v[76:77], v[78:79]
	v_pk_fma_f32 v[68:69], v[72:73], v[72:73], v[68:69]
	v_mov_b32_e32 v82, v59
	v_mov_b32_e32 v83, v57
	v_pk_fma_f32 v[70:71], v[80:81], v[80:81], v[70:71]
	v_pk_fma_f32 v[68:69], v[74:75], v[74:75], v[68:69]
	v_pk_fma_f32 v[70:71], v[82:83], v[82:83], v[70:71]
	v_add_f32_e32 v51, v68, v69
	v_add_f32_e32 v51, v71, v51
	v_add_f32_e32 v51, v70, v51
	ds_bpermute_b32 v68, v44, v51
	s_waitcnt lgkmcnt(0)
	v_add_f32_e32 v51, v51, v68
	ds_bpermute_b32 v68, v45, v51
	s_waitcnt lgkmcnt(0)
	v_add_f32_e32 v51, v51, v68
	ds_bpermute_b32 v68, v46, v51
	s_waitcnt lgkmcnt(0)
	v_add_f32_e32 v51, v51, v68
	ds_bpermute_b32 v68, v47, v51
	s_waitcnt lgkmcnt(0)
	v_add_f32_e32 v51, v51, v68
	ds_bpermute_b32 v68, v48, v51
	s_waitcnt lgkmcnt(0)
	v_add_f32_e32 v51, v51, v68
	ds_bpermute_b32 v68, v49, v51
	s_waitcnt lgkmcnt(0)
	v_add_f32_e32 v51, v51, v68
	v_fmamk_f32 v51, v51, 0x3a800000, v50
	v_mul_f32_e32 v68, 0x4b800000, v51
	v_cmp_gt_f32_e32 vcc, s13, v51
	s_nop 1
	v_cndmask_b32_e32 v51, v51, v68, vcc
	v_rsq_f32_e32 v51, v51
	v_lshl_add_u64 v[68:69], v[18:19], 0, s[14:15]
	v_mul_f32_e32 v70, 0x45800000, v51
	v_cndmask_b32_e32 v70, v51, v70, vcc
	v_pk_mul_f32 v[60:61], v[70:71], v[60:61] op_sel_hi:[0,1]
	v_pk_mul_f32 v[72:73], v[70:71], v[52:53] op_sel_hi:[0,1]
	v_pk_mul_f32 v[62:63], v[70:71], v[62:63] op_sel_hi:[0,1]
	v_pk_mul_f32 v[74:75], v[70:71], v[54:55] op_sel_hi:[0,1]
	v_pk_mul_f32 v[64:65], v[70:71], v[64:65] op_sel_hi:[0,1]
	v_pk_mul_f32 v[76:77], v[70:71], v[56:57] op_sel_hi:[0,1]
	v_pk_mul_f32 v[66:67], v[70:71], v[66:67] op_sel_hi:[0,1]
	v_pk_mul_f32 v[70:71], v[70:71], v[58:59] op_sel_hi:[0,1]
	v_pk_mul_f32 v[52:53], v[12:13], v[60:61]
	v_pk_mul_f32 v[54:55], v[14:15], v[72:73]
	v_pk_mul_f32 v[56:57], v[8:9], v[62:63]
	v_pk_mul_f32 v[58:59], v[10:11], v[74:75]
	v_pk_mul_f32 v[60:61], v[4:5], v[64:65]
	v_pk_mul_f32 v[62:63], v[6:7], v[76:77]
	v_pk_mul_f32 v[64:65], v[0:1], v[66:67]
	v_pk_mul_f32 v[66:67], v[2:3], v[70:71]
	global_store_dwordx4 v[68:69], v[52:55], off sc1
	global_store_dwordx4 v[68:69], v[56:59], off offset:1024 sc1
	global_store_dwordx4 v[68:69], v[60:63], off offset:2048 sc1
	global_store_dwordx4 v[68:69], v[64:67], off offset:3072 sc1
	s_cbranch_scc1 .LBB0_439
; template <int MODE>
; __device__ __forceinline__ void rmsnorm_phase(const Params& p, const float* __restrict__ g, bf16* __restrict__ dstb, const int W) {
;     ...
;     for (int q = 0; q < NR; ++q) {
;       const int row = row0 + q * stride;
;       if (row >= T) break;
;       float ss = 0.f;
; #pragma unroll
;       for (int i = 0; i < 4; ++i) ss += v[q][i][0] * v[q][i][0] + v[q][i][1] * v[q][i][1] + v[q][i][2] * v[q][i][2] + v[q][i][3] * v[q][i][3];
;       ss = wave_sum(ss, lane);
;       const float rstd = rsqrtf(ss * (1.f / DM) + EPS);
; #pragma unroll
;       for (int i = 0; i < 4; ++i) {
;         if (MODE == 0) { u32x2 wr_ = {cvtpk(v[q][i][0], v[q][i][1]), cvtpk(v[q][i][2], v[q][i][3])};
;                          *reinterpret_cast<u32x2*>(resb + (size_t)row * DM + i * 256 + lane * 4) = wr_; }
;         f32x4 y = {v[q][i][0] * rstd * gv[i][0], v[q][i][1] * rstd * gv[i][1], v[q][i][2] * rstd * gv[i][2], v[q][i][3] * rstd * gv[i][3]};
;         if (MODE == 2) *reinterpret_cast<f32x4*>(p.out + (size_t)row * DM + i * 256 + lane * 4) = y;
	s_waitcnt vmcnt(15)
	v_and_b32_e32 v53, 0xffff0000, v42
	s_waitcnt vmcnt(14)
	v_and_b32_e32 v55, 0xffff0000, v40
	v_lshlrev_b32_e32 v52, 16, v42
	v_lshlrev_b32_e32 v54, 16, v40
	v_mov_b32_e32 v58, v53
	v_mov_b32_e32 v59, v55
	v_lshlrev_b32_e32 v42, 16, v43
	v_lshlrev_b32_e32 v40, 16, v41
	v_mov_b32_e32 v56, v52
	v_mov_b32_e32 v57, v54
	v_pk_mul_f32 v[58:59], v[58:59], v[58:59]
	v_and_b32_e32 v43, 0xffff0000, v43
	v_and_b32_e32 v41, 0xffff0000, v41
	v_pk_fma_f32 v[56:57], v[56:57], v[56:57], v[58:59]
	v_mov_b32_e32 v58, v42
	v_mov_b32_e32 v59, v40
	v_mov_b32_e32 v60, v43
	v_mov_b32_e32 v61, v41
	v_pk_fma_f32 v[56:57], v[58:59], v[58:59], v[56:57]
	s_waitcnt vmcnt(13)
	v_and_b32_e32 v59, 0xffff0000, v38
	s_waitcnt vmcnt(12)
	v_and_b32_e32 v63, 0xffff0000, v36
	v_pk_fma_f32 v[56:57], v[60:61], v[60:61], v[56:57]
	v_lshlrev_b32_e32 v58, 16, v38
	v_lshlrev_b32_e32 v60, 16, v39
	v_and_b32_e32 v61, 0xffff0000, v39
	v_lshlrev_b32_e32 v62, 16, v36
	v_mov_b32_e32 v38, v59
	v_mov_b32_e32 v39, v63
	v_lshlrev_b32_e32 v64, 16, v37
	v_and_b32_e32 v65, 0xffff0000, v37
	v_mov_b32_e32 v36, v58
	v_mov_b32_e32 v37, v62
	v_pk_mul_f32 v[38:39], v[38:39], v[38:39]
	v_mov_b32_e32 v66, v61
	v_pk_fma_f32 v[36:37], v[36:37], v[36:37], v[38:39]
	v_mov_b32_e32 v38, v60
	v_mov_b32_e32 v39, v64
	v_mov_b32_e32 v67, v65
	v_pk_fma_f32 v[36:37], v[38:39], v[38:39], v[36:37]
	v_add_f32_e32 v38, v56, v57
	v_pk_fma_f32 v[36:37], v[66:67], v[66:67], v[36:37]
	s_ashr_i32 s1, s0, 31
	v_add_f32_e32 v36, v38, v36
	v_add_f32_e32 v36, v36, v37
	ds_bpermute_b32 v37, v44, v36
	s_lshl_b64 s[14:15], s[0:1], 12
	v_lshl_add_u64 v[56:57], v[18:19], 0, s[14:15]
	s_waitcnt lgkmcnt(0)
	v_add_f32_e32 v36, v36, v37
	ds_bpermute_b32 v37, v45, v36
	s_waitcnt lgkmcnt(0)
	v_add_f32_e32 v36, v36, v37
	ds_bpermute_b32 v37, v46, v36
	s_waitcnt lgkmcnt(0)
	v_add_f32_e32 v36, v36, v37
	ds_bpermute_b32 v37, v47, v36
	s_waitcnt lgkmcnt(0)
	v_add_f32_e32 v36, v36, v37
	ds_bpermute_b32 v37, v48, v36
	s_waitcnt lgkmcnt(0)
	v_add_f32_e32 v36, v36, v37
	ds_bpermute_b32 v37, v49, v36
	s_waitcnt lgkmcnt(0)
	v_add_f32_e32 v36, v36, v37
	v_fmamk_f32 v36, v36, 0x3a800000, v50
	v_mul_f32_e32 v37, 0x4b800000, v36
	v_cmp_gt_f32_e32 vcc, s13, v36
	s_nop 1
	v_cndmask_b32_e32 v36, v36, v37, vcc
	v_rsq_f32_e32 v36, v36
	s_nop 0
	v_mul_f32_e32 v37, 0x45800000, v36
	v_cndmask_b32_e32 v66, v36, v37, vcc
	v_pk_mul_f32 v[36:37], v[66:67], v[52:53] op_sel_hi:[0,1]
	v_pk_mul_f32 v[38:39], v[66:67], v[42:43] op_sel_hi:[0,1]
	v_pk_mul_f32 v[36:37], v[12:13], v[36:37]
	v_pk_mul_f32 v[38:39], v[14:15], v[38:39]
	global_store_dwordx4 v[56:57], v[36:39], off sc1
	s_andn2_b64 vcc, exec, s[8:9]
	s_nop 0
	v_pk_mul_f32 v[36:37], v[66:67], v[54:55] op_sel_hi:[0,1]
	v_pk_mul_f32 v[38:39], v[66:67], v[40:41] op_sel_hi:[0,1]
	v_pk_mul_f32 v[36:37], v[8:9], v[36:37]
	v_pk_mul_f32 v[38:39], v[10:11], v[38:39]
	global_store_dwordx4 v[56:57], v[36:39], off offset:1024 sc1
	s_nop 1
	v_pk_mul_f32 v[36:37], v[66:67], v[58:59] op_sel_hi:[0,1]
	v_pk_mul_f32 v[38:39], v[66:67], v[60:61] op_sel_hi:[0,1]
	v_pk_mul_f32 v[36:37], v[4:5], v[36:37]
	v_pk_mul_f32 v[38:39], v[6:7], v[38:39]
	global_store_dwordx4 v[56:57], v[36:39], off offset:2048 sc1
	s_nop 1
	v_pk_mul_f32 v[36:37], v[66:67], v[62:63] op_sel_hi:[0,1]
	v_pk_mul_f32 v[38:39], v[66:67], v[64:65] op_sel_hi:[0,1]
	v_pk_mul_f32 v[36:37], v[0:1], v[36:37]
	v_pk_mul_f32 v[38:39], v[2:3], v[38:39]
	global_store_dwordx4 v[56:57], v[36:39], off offset:3072 sc1
	s_cbranch_vccnz .LBB0_439
; template <int MODE>
; __device__ __forceinline__ void rmsnorm_phase(const Params& p, const float* __restrict__ g, bf16* __restrict__ dstb, const int W) {
;     ...
;     for (int q = 0; q < NR; ++q) {
;       const int row = row0 + q * stride;
;       if (row >= T) break;
;       float ss = 0.f;
; #pragma unroll
;       for (int i = 0; i < 4; ++i) ss += v[q][i][0] * v[q][i][0] + v[q][i][1] * v[q][i][1] + v[q][i][2] * v[q][i][2] + v[q][i][3] * v[q][i][3];
;       ss = wave_sum(ss, lane);
;       const float rstd = rsqrtf(ss * (1.f / DM) + EPS);
; #pragma unroll
;       for (int i = 0; i < 4; ++i) {
;         if (MODE == 0) { u32x2 wr_ = {cvtpk(v[q][i][0], v[q][i][1]), cvtpk(v[q][i][2], v[q][i][3])};
;                          *reinterpret_cast<u32x2*>(resb + (size_t)row * DM + i * 256 + lane * 4) = wr_; }
;         f32x4 y = {v[q][i][0] * rstd * gv[i][0], v[q][i][1] * rstd * gv[i][1], v[q][i][2] * rstd * gv[i][2], v[q][i][3] * rstd * gv[i][3]};
;         if (MODE == 2) *reinterpret_cast<f32x4*>(p.out + (size_t)row * DM + i * 256 + lane * 4) = y;
	s_waitcnt vmcnt(15)
	v_and_b32_e32 v37, 0xffff0000, v34
	s_waitcnt vmcnt(14)
	v_and_b32_e32 v39, 0xffff0000, v32
	v_lshlrev_b32_e32 v36, 16, v34
	v_lshlrev_b32_e32 v38, 16, v32
	s_waitcnt vmcnt(13)
	v_lshlrev_b32_e32 v40, 16, v30
	v_and_b32_e32 v41, 0xffff0000, v30
	v_lshlrev_b32_e32 v42, 16, v31
	v_and_b32_e32 v43, 0xffff0000, v31
	v_mov_b32_e32 v30, v37
	v_mov_b32_e32 v31, v39
	v_lshlrev_b32_e32 v34, 16, v35
	v_lshlrev_b32_e32 v32, 16, v33
	s_waitcnt vmcnt(12)
	v_lshlrev_b32_e32 v52, 16, v28
	v_and_b32_e32 v53, 0xffff0000, v28
	v_lshlrev_b32_e32 v54, 16, v29
	v_and_b32_e32 v55, 0xffff0000, v29
	v_mov_b32_e32 v28, v36
	v_mov_b32_e32 v29, v38
	v_pk_mul_f32 v[30:31], v[30:31], v[30:31]
	v_and_b32_e32 v35, 0xffff0000, v35
	v_and_b32_e32 v33, 0xffff0000, v33
	v_pk_fma_f32 v[28:29], v[28:29], v[28:29], v[30:31]
	v_mov_b32_e32 v30, v34
	v_mov_b32_e32 v31, v32
	v_pk_fma_f32 v[28:29], v[30:31], v[30:31], v[28:29]
	v_mov_b32_e32 v30, v35
	v_mov_b32_e32 v31, v33
	v_mov_b32_e32 v56, v41
	v_mov_b32_e32 v57, v53
	v_pk_fma_f32 v[28:29], v[30:31], v[30:31], v[28:29]
	v_mov_b32_e32 v30, v40
	v_mov_b32_e32 v31, v52
	v_pk_mul_f32 v[56:57], v[56:57], v[56:57]
	v_add_f32_e32 v28, v28, v29
	v_pk_fma_f32 v[30:31], v[30:31], v[30:31], v[56:57]
	v_mov_b32_e32 v56, v42
	v_mov_b32_e32 v57, v54
	v_pk_fma_f32 v[30:31], v[56:57], v[56:57], v[30:31]
	v_mov_b32_e32 v56, v43
	v_mov_b32_e32 v57, v55
	v_pk_fma_f32 v[30:31], v[56:57], v[56:57], v[30:31]
	s_ashr_i32 s7, s6, 31
	v_add_f32_e32 v28, v28, v30
	v_add_f32_e32 v28, v28, v31
	ds_bpermute_b32 v29, v44, v28
	s_lshl_b64 s[6:7], s[6:7], 12
	v_lshl_add_u64 v[58:59], v[18:19], 0, s[6:7]
	s_waitcnt lgkmcnt(0)
	v_add_f32_e32 v28, v28, v29
	ds_bpermute_b32 v29, v45, v28
	s_waitcnt lgkmcnt(0)
	v_add_f32_e32 v28, v28, v29
	ds_bpermute_b32 v29, v46, v28
	s_waitcnt lgkmcnt(0)
	v_add_f32_e32 v28, v28, v29
	ds_bpermute_b32 v29, v47, v28
	s_waitcnt lgkmcnt(0)
	v_add_f32_e32 v28, v28, v29
	ds_bpermute_b32 v29, v48, v28
	s_waitcnt lgkmcnt(0)
	v_add_f32_e32 v28, v28, v29
	ds_bpermute_b32 v29, v49, v28
	s_waitcnt lgkmcnt(0)
	v_add_f32_e32 v28, v28, v29
	v_fmamk_f32 v28, v28, 0x3a800000, v50
	v_mul_f32_e32 v29, 0x4b800000, v28
	v_cmp_gt_f32_e32 vcc, s13, v28
	s_nop 1
	v_cndmask_b32_e32 v28, v28, v29, vcc
	v_rsq_f32_e32 v28, v28
	s_nop 0
	v_mul_f32_e32 v29, 0x45800000, v28
	v_cndmask_b32_e32 v56, v28, v29, vcc
	v_pk_mul_f32 v[28:29], v[56:57], v[36:37] op_sel_hi:[0,1]
	v_pk_mul_f32 v[30:31], v[56:57], v[34:35] op_sel_hi:[0,1]
	v_pk_mul_f32 v[28:29], v[12:13], v[28:29]
	v_pk_mul_f32 v[30:31], v[14:15], v[30:31]
	global_store_dwordx4 v[58:59], v[28:31], off sc1
	s_andn2_b64 vcc, exec, s[4:5]
	s_nop 0
	v_pk_mul_f32 v[28:29], v[56:57], v[38:39] op_sel_hi:[0,1]
	v_pk_mul_f32 v[30:31], v[56:57], v[32:33] op_sel_hi:[0,1]
	v_pk_mul_f32 v[28:29], v[8:9], v[28:29]
	v_pk_mul_f32 v[30:31], v[10:11], v[30:31]
	global_store_dwordx4 v[58:59], v[28:31], off offset:1024 sc1
	s_nop 1
	v_pk_mul_f32 v[28:29], v[56:57], v[40:41] op_sel_hi:[0,1]
	v_pk_mul_f32 v[30:31], v[56:57], v[42:43] op_sel_hi:[0,1]
	v_pk_mul_f32 v[28:29], v[4:5], v[28:29]
	v_pk_mul_f32 v[30:31], v[6:7], v[30:31]
	global_store_dwordx4 v[58:59], v[28:31], off offset:2048 sc1
	s_nop 1
	v_pk_mul_f32 v[28:29], v[56:57], v[52:53] op_sel_hi:[0,1]
	v_pk_mul_f32 v[30:31], v[56:57], v[54:55] op_sel_hi:[0,1]
	v_pk_mul_f32 v[28:29], v[0:1], v[28:29]
	v_pk_mul_f32 v[30:31], v[2:3], v[30:31]
	global_store_dwordx4 v[58:59], v[28:31], off offset:3072 sc1
	s_cbranch_vccnz .LBB0_439
	s_waitcnt vmcnt(15)
	v_and_b32_e32 v29, 0xffff0000, v26
	s_waitcnt vmcnt(14)
	v_and_b32_e32 v31, 0xffff0000, v24
	v_lshlrev_b32_e32 v28, 16, v26
	v_lshlrev_b32_e32 v30, 16, v24
	s_waitcnt vmcnt(13)
	v_lshlrev_b32_e32 v32, 16, v22
	v_and_b32_e32 v33, 0xffff0000, v22
	v_lshlrev_b32_e32 v34, 16, v23
	v_and_b32_e32 v35, 0xffff0000, v23
	v_mov_b32_e32 v22, v29
	v_mov_b32_e32 v23, v31
	v_lshlrev_b32_e32 v26, 16, v27
	v_lshlrev_b32_e32 v24, 16, v25
	s_waitcnt vmcnt(12)
	v_lshlrev_b32_e32 v36, 16, v20
	v_and_b32_e32 v37, 0xffff0000, v20
	v_lshlrev_b32_e32 v38, 16, v21
	v_and_b32_e32 v39, 0xffff0000, v21
	v_mov_b32_e32 v20, v28
	v_mov_b32_e32 v21, v30
	v_pk_mul_f32 v[22:23], v[22:23], v[22:23]
	v_and_b32_e32 v27, 0xffff0000, v27
	v_and_b32_e32 v25, 0xffff0000, v25
	v_pk_fma_f32 v[20:21], v[20:21], v[20:21], v[22:23]
	v_mov_b32_e32 v22, v26
	v_mov_b32_e32 v23, v24
	v_pk_fma_f32 v[20:21], v[22:23], v[22:23], v[20:21]
	v_mov_b32_e32 v22, v27
	v_mov_b32_e32 v23, v25
	v_mov_b32_e32 v40, v33
	v_mov_b32_e32 v41, v37
	v_pk_fma_f32 v[20:21], v[22:23], v[22:23], v[20:21]
	v_mov_b32_e32 v22, v32
	v_mov_b32_e32 v23, v36
	v_pk_mul_f32 v[40:41], v[40:41], v[40:41]
	v_add_f32_e32 v20, v20, v21
	v_pk_fma_f32 v[22:23], v[22:23], v[22:23], v[40:41]
	v_mov_b32_e32 v40, v34
	v_mov_b32_e32 v41, v38
	v_pk_fma_f32 v[22:23], v[40:41], v[40:41], v[22:23]
	v_mov_b32_e32 v40, v35
	v_mov_b32_e32 v41, v39
	v_pk_fma_f32 v[22:23], v[40:41], v[40:41], v[22:23]
	s_ashr_i32 s3, s2, 31
	v_add_f32_e32 v20, v20, v22
	v_add_f32_e32 v20, v20, v23
	ds_bpermute_b32 v21, v44, v20
	s_lshl_b64 s[2:3], s[2:3], 12
	v_lshl_add_u64 v[42:43], v[18:19], 0, s[2:3]
	s_waitcnt lgkmcnt(0)
	v_add_f32_e32 v20, v20, v21
	ds_bpermute_b32 v21, v45, v20
	s_waitcnt lgkmcnt(0)
	v_add_f32_e32 v20, v20, v21
	ds_bpermute_b32 v21, v46, v20
	s_waitcnt lgkmcnt(0)
	v_add_f32_e32 v20, v20, v21
	ds_bpermute_b32 v21, v47, v20
	s_waitcnt lgkmcnt(0)
	v_add_f32_e32 v20, v20, v21
	ds_bpermute_b32 v21, v48, v20
	s_waitcnt lgkmcnt(0)
	v_add_f32_e32 v20, v20, v21
	ds_bpermute_b32 v21, v49, v20
	s_waitcnt lgkmcnt(0)
	v_add_f32_e32 v20, v20, v21
	v_fmamk_f32 v20, v20, 0x3a800000, v50
	v_mul_f32_e32 v21, 0x4b800000, v20
	v_cmp_gt_f32_e32 vcc, s13, v20
	s_nop 1
	v_cndmask_b32_e32 v20, v20, v21, vcc
	v_rsq_f32_e32 v20, v20
	s_nop 0
	v_mul_f32_e32 v21, 0x45800000, v20
	v_cndmask_b32_e32 v40, v20, v21, vcc
	v_pk_mul_f32 v[20:21], v[40:41], v[28:29] op_sel_hi:[0,1]
	v_pk_mul_f32 v[22:23], v[40:41], v[26:27] op_sel_hi:[0,1]
	v_pk_mul_f32 v[20:21], v[12:13], v[20:21]
	v_pk_mul_f32 v[22:23], v[14:15], v[22:23]
	global_store_dwordx4 v[42:43], v[20:23], off sc1
	s_nop 1
	v_pk_mul_f32 v[20:21], v[40:41], v[30:31] op_sel_hi:[0,1]
	v_pk_mul_f32 v[22:23], v[40:41], v[24:25] op_sel_hi:[0,1]
	v_pk_mul_f32 v[20:21], v[8:9], v[20:21]
	v_pk_mul_f32 v[22:23], v[10:11], v[22:23]
	global_store_dwordx4 v[42:43], v[20:23], off offset:1024 sc1
	s_nop 1
	v_pk_mul_f32 v[20:21], v[40:41], v[32:33] op_sel_hi:[0,1]
	v_pk_mul_f32 v[22:23], v[40:41], v[34:35] op_sel_hi:[0,1]
	v_pk_mul_f32 v[20:21], v[4:5], v[20:21]
	v_pk_mul_f32 v[22:23], v[6:7], v[22:23]
	global_store_dwordx4 v[42:43], v[20:23], off offset:2048 sc1
	s_nop 1
	v_pk_mul_f32 v[20:21], v[40:41], v[36:37] op_sel_hi:[0,1]
	v_pk_mul_f32 v[22:23], v[40:41], v[38:39] op_sel_hi:[0,1]
	v_pk_mul_f32 v[20:21], v[0:1], v[20:21]
	v_pk_mul_f32 v[22:23], v[2:3], v[22:23]
	global_store_dwordx4 v[42:43], v[20:23], off offset:3072 sc1
	s_branch .LBB0_439
